# second-dma-of-each-stage-via-second-lane-offset-vgpr-up-cgu
# speedup vs baseline: 1.0103x; 1.0005x over previous
; #define PG8_STAGE(bufoff, gbase, hoff, imm) do { _Pragma("unroll") for (int _i = 0; _i < 2; ++_i) { \
;         asm volatile("s_mov_b32 m0, %0\n\ts_nop 0\n\tglobal_load_lds_dwordx4 %1, %2" \
;             :: "s"(lds0 + (unsigned)((bufoff) + _i * 8192)), "v"(voff0), "s"((const char*)(gbase) + (size_t)(hoff) + (size_t)(_i * 8192)) : "memory"); } } while (0)
; #define PG8_LDA(dst, b, h) do { _Pragma("unroll") for (int m = 0; m < 4; ++m) _Pragma("unroll") for (int k = 0; k < 2; ++k) dst[m][k] = *(const LAS bf16x8*)(lds + PG8_SA(b, h) + aoff + m * 2048 + k * 1024); } while (0)
; #define PG8_LDB(dst, b, h) do { _Pragma("unroll") for (int n = 0; n < 2; ++n) _Pragma("unroll") for (int k = 0; k < 2; ++k) dst[n][k] = *(const LAS bf16x8*)(lds + PG8_SB(b, h) + boff + n * 2048 + k * 1024); } while (0)
; #define PG8_WAIT_V(n) asm volatile("s_waitcnt vmcnt(" #n ")" ::: "memory")
; #define PG8_WAIT_L(n) asm volatile("s_waitcnt lgkmcnt(" #n ")" ::: "memory")
; #define PG8_BAR __builtin_amdgcn_s_barrier()
; template <class Epi>
; __device__ __forceinline__ void gemm_phase(LAS unsigned char* lds, const Gemm g, const StaticOrder& S, const Epi& E) {
;     ...
;         const bool has_next = S.next(ui + 1, nxt);
;         const char* nA = has_next ? (const char*)g.A + (size_t)nxt.pm * tstepA + (size_t)(nxt.pn >> g.gshift) * g.gstride : cA;
;         const char* nB = has_next ? (const char*)g.Bt + (size_t)nxt.pn * tstepB : cB;
;         for (int t = 0; t < nt; t += 2) {
;             const bool last = (t == nt - 2);
;             if (last) E.pre(cur, wid, lane, (unsigned)(size_t)(lds + STAGE_BYTES));
;             const char* aT = cA + (size_t)t * KS;
;             const char* a2 = last ? nA : aT + 2 * KS; const char* b2 = last ? nB : cB + (size_t)(t + 2) * KS;
;             PG8_LDB(B0, 0, 0); PG8_SCHED; PG8_LDA(At, 0, 0); PG8_STAGE(PG8_SA(1, 1), aT + KS, hA, 0);
;             PG8_WAIT_L(8); PG8_BAR; PG8_WAIT_L(0); PG8_MMA(0, 0, At, B0); PG8_BAR; PG8_SCHED;
;             PG8_LDB(B1, 0, 1); PG8_STAGE(PG8_SB(0, 0), b2, 0, 0);
;             PG8_BAR; PG8_WAIT_L(0); PG8_MMA(0, 1, At, B1); PG8_BAR;
;             PG8_LDA(At, 0, 1); PG8_STAGE(PG8_SA(0, 0), a2, 0, 0);
;             PG8_BAR; PG8_WAIT_L(0); PG8_MMA(1, 0, At, B0); PG8_BAR; PG8_SCHED;
;             PG8_STAGE(PG8_SB(0, 1), b2, hB, 0);
;             PG8_WAIT_V(6); PG8_BAR; PG8_MMA(1, 1, At, B1); PG8_BAR;
.LBB0_505:
	s_ashr_i32 s71, s70, 31
	v_cmp_lt_i64_e32 vcc, s[8:9], v[194:195]
	s_lshl_b64 s[8:9], s[70:71], 20
	s_add_u32 s72, s16, s8
	s_addc_u32 s73, s17, s9
	s_and_b64 s[8:9], vcc, exec
	s_cselect_b32 s51, s73, s79
	s_cselect_b32 s71, s72, s78
	s_ashr_i32 s69, s68, 31
	s_lshl_b64 s[8:9], s[68:69], 20
	s_add_u32 s74, s21, s8
	s_addc_u32 s75, s22, s9
	s_and_b64 s[8:9], vcc, exec
	s_cselect_b32 s69, s75, s81
	s_cselect_b32 s62, s74, s80
	s_lshl_b32 s8, s0, 7
	s_ashr_i32 s9, s8, 31
	s_lshl_b64 s[0:1], s[8:9], 2
	s_add_u32 s76, s12, s0
	s_addc_u32 s77, s97, s1
	s_add_u32 s9, s80, 0x8000
	s_addc_u32 s63, s81, 0
	s_mov_b32 s0, -2
	v_add_u32_e32 v188, 0x2000, v168
	s_mov_b64 s[84:85], 0
	ds_read_b128 v[128:131], v202
	ds_read_b128 v[132:135], v202 offset:1024
	ds_read_b128 v[136:139], v202 offset:2048
	ds_read_b128 v[140:143], v202 offset:3072
	s_add_u32 s80, s78, 0x8000
	s_addc_u32 s81, s79, 0
	s_and_b64 s[82:83], s[84:85], exec
	s_cselect_b32 s83, s51, s81
	s_cselect_b32 s82, s71, s80
	ds_read_b128 v[144:147], v203
	ds_read_b128 v[148:151], v203 offset:1024
	ds_read_b128 v[152:155], v203 offset:2048
	ds_read_b128 v[156:159], v203 offset:3072
	ds_read_b128 v[160:163], v203 offset:4096
	ds_read_b128 v[164:167], v203 offset:5120
	ds_read_b128 v[204:207], v203 offset:6144
	ds_read_b128 v[208:211], v203 offset:7168
	s_add_u32 s48, s78, 0x84000
	s_addc_u32 s49, s79, 0
	s_mov_b32 m0, s87
	s_nop 0
	global_load_lds_dwordx4 v168, s[48:49]
	s_mov_b32 m0, s96
	s_nop 0
	global_load_lds_dwordx4 v188, s[48:49]
	s_waitcnt lgkmcnt(8)
	s_waitcnt vmcnt(10)
	s_barrier
	s_waitcnt lgkmcnt(7)
	v_mfma_f32_16x16x32_bf16 v[96:99], v[128:131], v[144:147], 0
	v_mfma_f32_16x16x32_bf16 v[44:47], v[136:139], v[144:147], 0
	s_waitcnt lgkmcnt(5)
	v_mfma_f32_16x16x32_bf16 v[92:95], v[128:131], v[152:155], 0
	v_mfma_f32_16x16x32_bf16 v[40:43], v[136:139], v[152:155], 0
	s_waitcnt lgkmcnt(3)
	v_mfma_f32_16x16x32_bf16 v[84:87], v[128:131], v[160:163], 0
	v_mfma_f32_16x16x32_bf16 v[36:39], v[136:139], v[160:163], 0
	s_waitcnt lgkmcnt(1)
	v_mfma_f32_16x16x32_bf16 v[124:127], v[128:131], v[204:207], 0
	v_mfma_f32_16x16x32_bf16 v[120:123], v[136:139], v[204:207], 0
	v_mfma_f32_16x16x32_bf16 v[96:99], v[132:135], v[148:151], v[96:99]
	v_mfma_f32_16x16x32_bf16 v[44:47], v[140:143], v[148:151], v[44:47]
	v_mfma_f32_16x16x32_bf16 v[92:95], v[132:135], v[156:159], v[92:95]
	v_mfma_f32_16x16x32_bf16 v[40:43], v[140:143], v[156:159], v[40:43]
	v_mfma_f32_16x16x32_bf16 v[84:87], v[132:135], v[164:167], v[84:87]
	v_mfma_f32_16x16x32_bf16 v[36:39], v[140:143], v[164:167], v[36:39]
	s_waitcnt lgkmcnt(0)
	v_mfma_f32_16x16x32_bf16 v[124:127], v[132:135], v[208:211], v[124:127]
	v_mfma_f32_16x16x32_bf16 v[120:123], v[140:143], v[208:211], v[120:123]
	s_barrier
	ds_read_b128 v[212:215], v202 offset:16384
	ds_read_b128 v[236:239], v202 offset:17408
	ds_read_b128 v[240:243], v202 offset:18432
	ds_read_b128 v[244:247], v202 offset:19456
	s_and_b64 s[48:49], s[84:85], exec
	s_cselect_b32 s78, s62, s9
	s_cselect_b32 s79, s69, s63
	s_mov_b32 m0, s25
	s_nop 0
	global_load_lds_dwordx4 v168, s[78:79]
	s_mov_b32 m0, s26
	s_nop 0
	global_load_lds_dwordx4 v188, s[78:79]
	s_waitcnt vmcnt(10)
	s_barrier
	s_waitcnt lgkmcnt(3)
	v_mfma_f32_16x16x32_bf16 v[80:83], v[212:215], v[144:147], 0
	s_waitcnt lgkmcnt(1)
	v_mfma_f32_16x16x32_bf16 v[32:35], v[240:243], v[144:147], 0
	v_mfma_f32_16x16x32_bf16 v[76:79], v[212:215], v[152:155], 0
	v_mfma_f32_16x16x32_bf16 v[28:31], v[240:243], v[152:155], 0
	v_mfma_f32_16x16x32_bf16 v[72:75], v[212:215], v[160:163], 0
	v_mfma_f32_16x16x32_bf16 v[24:27], v[240:243], v[160:163], 0
	v_mfma_f32_16x16x32_bf16 v[116:119], v[212:215], v[204:207], 0
	v_mfma_f32_16x16x32_bf16 v[112:115], v[240:243], v[204:207], 0
	v_mfma_f32_16x16x32_bf16 v[80:83], v[236:239], v[148:151], v[80:83]
	s_waitcnt lgkmcnt(0)
	v_mfma_f32_16x16x32_bf16 v[32:35], v[244:247], v[148:151], v[32:35]
	v_mfma_f32_16x16x32_bf16 v[76:79], v[236:239], v[156:159], v[76:79]
	v_mfma_f32_16x16x32_bf16 v[28:31], v[244:247], v[156:159], v[28:31]
	v_mfma_f32_16x16x32_bf16 v[72:75], v[236:239], v[164:167], v[72:75]
	v_mfma_f32_16x16x32_bf16 v[24:27], v[244:247], v[164:167], v[24:27]
	v_mfma_f32_16x16x32_bf16 v[116:119], v[236:239], v[208:211], v[116:119]
	v_mfma_f32_16x16x32_bf16 v[112:115], v[244:247], v[208:211], v[112:115]
	s_barrier
	ds_read_b128 v[144:147], v203 offset:16384
	ds_read_b128 v[148:151], v203 offset:17408
	ds_read_b128 v[152:155], v203 offset:18432
	ds_read_b128 v[156:159], v203 offset:19456
	ds_read_b128 v[160:163], v203 offset:20480
	ds_read_b128 v[164:167], v203 offset:21504
	ds_read_b128 v[204:207], v203 offset:22528
	ds_read_b128 v[208:211], v203 offset:23552
	s_mov_b32 m0, s24
	s_nop 0
	global_load_lds_dwordx4 v168, s[82:83]
	s_mov_b32 m0, s27
	s_nop 0
	global_load_lds_dwordx4 v188, s[82:83]
	s_barrier
	s_waitcnt lgkmcnt(7)
	v_mfma_f32_16x16x32_bf16 v[68:71], v[128:131], v[144:147], 0
	v_mfma_f32_16x16x32_bf16 v[20:23], v[136:139], v[144:147], 0
	s_waitcnt lgkmcnt(5)
	v_mfma_f32_16x16x32_bf16 v[64:67], v[128:131], v[152:155], 0
	v_mfma_f32_16x16x32_bf16 v[16:19], v[136:139], v[152:155], 0
	s_waitcnt lgkmcnt(3)
	v_mfma_f32_16x16x32_bf16 v[60:63], v[128:131], v[160:163], 0
	v_mfma_f32_16x16x32_bf16 v[12:15], v[136:139], v[160:163], 0
	s_waitcnt lgkmcnt(1)
	v_mfma_f32_16x16x32_bf16 v[108:111], v[128:131], v[204:207], 0
	v_mfma_f32_16x16x32_bf16 v[104:107], v[136:139], v[204:207], 0
	v_mfma_f32_16x16x32_bf16 v[68:71], v[132:135], v[148:151], v[68:71]
	v_mfma_f32_16x16x32_bf16 v[20:23], v[140:143], v[148:151], v[20:23]
	v_mfma_f32_16x16x32_bf16 v[64:67], v[132:135], v[156:159], v[64:67]
	v_mfma_f32_16x16x32_bf16 v[16:19], v[140:143], v[156:159], v[16:19]
	v_mfma_f32_16x16x32_bf16 v[60:63], v[132:135], v[164:167], v[60:63]
	v_mfma_f32_16x16x32_bf16 v[12:15], v[140:143], v[164:167], v[12:15]
	s_waitcnt lgkmcnt(0)
	v_mfma_f32_16x16x32_bf16 v[108:111], v[132:135], v[208:211], v[108:111]
	v_mfma_f32_16x16x32_bf16 v[104:107], v[140:143], v[208:211], v[104:107]
	s_barrier
; #define PG8_STAGE(bufoff, gbase, hoff, imm) do { _Pragma("unroll") for (int _i = 0; _i < 2; ++_i) { \
;         asm volatile("s_mov_b32 m0, %0\n\ts_nop 0\n\tglobal_load_lds_dwordx4 %1, %2" \
;             :: "s"(lds0 + (unsigned)((bufoff) + _i * 8192)), "v"(voff0), "s"((const char*)(gbase) + (size_t)(hoff) + (size_t)(_i * 8192)) : "memory"); } } while (0)
; #define PG8_LDA(dst, b, h) do { _Pragma("unroll") for (int m = 0; m < 4; ++m) _Pragma("unroll") for (int k = 0; k < 2; ++k) dst[m][k] = *(const LAS bf16x8*)(lds + PG8_SA(b, h) + aoff + m * 2048 + k * 1024); } while (0)
; #define PG8_LDB(dst, b, h) do { _Pragma("unroll") for (int n = 0; n < 2; ++n) _Pragma("unroll") for (int k = 0; k < 2; ++k) dst[n][k] = *(const LAS bf16x8*)(lds + PG8_SB(b, h) + boff + n * 2048 + k * 1024); } while (0)
; #define PG8_WAIT_V(n) asm volatile("s_waitcnt vmcnt(" #n ")" ::: "memory")
; #define PG8_WAIT_L(n) asm volatile("s_waitcnt lgkmcnt(" #n ")" ::: "memory")
; #define PG8_BAR __builtin_amdgcn_s_barrier()
; template <class Epi>
; __device__ __forceinline__ void gemm_phase(LAS unsigned char* lds, const Gemm g, const StaticOrder& S, const Epi& E) {
;     ...
;             PG8_LDB(B0, 0, 0); PG8_SCHED; PG8_LDA(At, 0, 0); PG8_STAGE(PG8_SA(1, 1), aT + KS, hA, 0);
;             PG8_WAIT_L(8); PG8_BAR; PG8_WAIT_L(0); PG8_MMA(0, 0, At, B0); PG8_BAR; PG8_SCHED;
;             PG8_LDB(B1, 0, 1); PG8_STAGE(PG8_SB(0, 0), b2, 0, 0);
;             PG8_BAR; PG8_WAIT_L(0); PG8_MMA(0, 1, At, B1); PG8_BAR;
;             PG8_LDA(At, 0, 1); PG8_STAGE(PG8_SA(0, 0), a2, 0, 0);
;             PG8_BAR; PG8_WAIT_L(0); PG8_MMA(1, 0, At, B0); PG8_BAR; PG8_SCHED;
;             PG8_STAGE(PG8_SB(0, 1), b2, hB, 0);
;             PG8_WAIT_V(6); PG8_BAR; PG8_MMA(1, 1, At, B1); PG8_BAR;
;             PG8_LDB(B0, 1, 0); PG8_SCHED; PG8_LDA(At, 1, 0); PG8_STAGE(PG8_SA(0, 1), a2, hA, 0);
;             PG8_WAIT_L(8); PG8_BAR; PG8_WAIT_L(0); PG8_MMA(0, 0, At, B0); PG8_BAR; PG8_SCHED;
;             PG8_LDB(B1, 1, 1); PG8_STAGE(PG8_SB(1, 0), b2 + KS, 0, 0);
;             PG8_BAR; PG8_WAIT_L(0); PG8_MMA(0, 1, At, B1); PG8_BAR;
;             PG8_LDA(At, 1, 1); PG8_STAGE(PG8_SA(1, 0), a2 + KS, 0, 0);
;             PG8_BAR; PG8_WAIT_L(0); PG8_MMA(1, 0, At, B0); PG8_BAR; PG8_SCHED;
;             PG8_STAGE(PG8_SB(1, 1), b2 + KS, hB, 0);
;             PG8_WAIT_V(6); PG8_BAR; PG8_MMA(1, 1, At, B1); PG8_BAR;
	s_add_u32 s48, s78, 0x80000
	s_addc_u32 s49, s79, 0
	s_mov_b32 m0, s28
	s_nop 0
	global_load_lds_dwordx4 v168, s[48:49]
	s_mov_b32 m0, s29
	s_nop 0
	global_load_lds_dwordx4 v188, s[48:49]
	s_waitcnt vmcnt(10)
	s_barrier
	v_mfma_f32_16x16x32_bf16 v[56:59], v[212:215], v[144:147], 0
	v_mfma_f32_16x16x32_bf16 v[8:11], v[240:243], v[144:147], 0
	v_mfma_f32_16x16x32_bf16 v[52:55], v[212:215], v[152:155], 0
	v_mfma_f32_16x16x32_bf16 v[4:7], v[240:243], v[152:155], 0
	v_mfma_f32_16x16x32_bf16 v[48:51], v[212:215], v[160:163], 0
	v_mfma_f32_16x16x32_bf16 v[0:3], v[240:243], v[160:163], 0
	v_mfma_f32_16x16x32_bf16 v[100:103], v[212:215], v[204:207], 0
	v_mfma_f32_16x16x32_bf16 v[88:91], v[240:243], v[204:207], 0
	v_mfma_f32_16x16x32_bf16 v[56:59], v[236:239], v[148:151], v[56:59]
	v_mfma_f32_16x16x32_bf16 v[8:11], v[244:247], v[148:151], v[8:11]
	v_mfma_f32_16x16x32_bf16 v[52:55], v[236:239], v[156:159], v[52:55]
	v_mfma_f32_16x16x32_bf16 v[4:7], v[244:247], v[156:159], v[4:7]
	v_mfma_f32_16x16x32_bf16 v[48:51], v[236:239], v[164:167], v[48:51]
	v_mfma_f32_16x16x32_bf16 v[0:3], v[244:247], v[164:167], v[0:3]
	v_mfma_f32_16x16x32_bf16 v[100:103], v[236:239], v[208:211], v[100:103]
	v_mfma_f32_16x16x32_bf16 v[88:91], v[244:247], v[208:211], v[88:91]
	s_barrier
	ds_read_b128 v[128:131], v202 offset:32768
	ds_read_b128 v[132:135], v202 offset:33792
	ds_read_b128 v[136:139], v202 offset:34816
	ds_read_b128 v[140:143], v202 offset:35840
	ds_read_b128 v[144:147], v203 offset:32768
	ds_read_b128 v[148:151], v203 offset:33792
	ds_read_b128 v[152:155], v203 offset:34816
	ds_read_b128 v[156:159], v203 offset:35840
	ds_read_b128 v[160:163], v203 offset:36864
	ds_read_b128 v[164:167], v203 offset:37888
	ds_read_b128 v[204:207], v203 offset:38912
	ds_read_b128 v[208:211], v203 offset:39936
	s_add_u32 s48, s82, 0x80000
	s_addc_u32 s49, s83, 0
	s_mov_b32 m0, s30
	s_nop 0
	global_load_lds_dwordx4 v168, s[48:49]
	s_mov_b32 m0, s34
	s_nop 0
	global_load_lds_dwordx4 v188, s[48:49]
	s_waitcnt lgkmcnt(8)
	s_waitcnt vmcnt(10)
	s_barrier
	s_waitcnt lgkmcnt(7)
	v_mfma_f32_16x16x32_bf16 v[96:99], v[128:131], v[144:147], v[96:99]
	v_mfma_f32_16x16x32_bf16 v[44:47], v[136:139], v[144:147], v[44:47]
	s_waitcnt lgkmcnt(5)
	v_mfma_f32_16x16x32_bf16 v[92:95], v[128:131], v[152:155], v[92:95]
	v_mfma_f32_16x16x32_bf16 v[40:43], v[136:139], v[152:155], v[40:43]
	s_waitcnt lgkmcnt(3)
	v_mfma_f32_16x16x32_bf16 v[84:87], v[128:131], v[160:163], v[84:87]
	v_mfma_f32_16x16x32_bf16 v[36:39], v[136:139], v[160:163], v[36:39]
	s_waitcnt lgkmcnt(1)
	v_mfma_f32_16x16x32_bf16 v[124:127], v[128:131], v[204:207], v[124:127]
	v_mfma_f32_16x16x32_bf16 v[120:123], v[136:139], v[204:207], v[120:123]
	v_mfma_f32_16x16x32_bf16 v[96:99], v[132:135], v[148:151], v[96:99]
	v_mfma_f32_16x16x32_bf16 v[44:47], v[140:143], v[148:151], v[44:47]
	v_mfma_f32_16x16x32_bf16 v[92:95], v[132:135], v[156:159], v[92:95]
	v_mfma_f32_16x16x32_bf16 v[40:43], v[140:143], v[156:159], v[40:43]
	v_mfma_f32_16x16x32_bf16 v[84:87], v[132:135], v[164:167], v[84:87]
	v_mfma_f32_16x16x32_bf16 v[36:39], v[140:143], v[164:167], v[36:39]
	s_waitcnt lgkmcnt(0)
	v_mfma_f32_16x16x32_bf16 v[124:127], v[132:135], v[208:211], v[124:127]
	v_mfma_f32_16x16x32_bf16 v[120:123], v[140:143], v[208:211], v[120:123]
	s_barrier
	ds_read_b128 v[212:215], v202 offset:49152
	ds_read_b128 v[236:239], v202 offset:50176
	ds_read_b128 v[240:243], v202 offset:51200
	ds_read_b128 v[244:247], v202 offset:52224
	s_add_u32 s48, s78, 0x4000
	s_addc_u32 s49, s79, 0
	s_mov_b32 m0, s38
	s_nop 0
	global_load_lds_dwordx4 v168, s[48:49]
	s_mov_b32 m0, s39
	s_nop 0
	global_load_lds_dwordx4 v188, s[48:49]
	s_waitcnt vmcnt(10)
	s_barrier
	s_waitcnt lgkmcnt(3)
	v_mfma_f32_16x16x32_bf16 v[80:83], v[212:215], v[144:147], v[80:83]
	s_waitcnt lgkmcnt(1)
	v_mfma_f32_16x16x32_bf16 v[32:35], v[240:243], v[144:147], v[32:35]
	v_mfma_f32_16x16x32_bf16 v[76:79], v[212:215], v[152:155], v[76:79]
	v_mfma_f32_16x16x32_bf16 v[28:31], v[240:243], v[152:155], v[28:31]
	v_mfma_f32_16x16x32_bf16 v[72:75], v[212:215], v[160:163], v[72:75]
	v_mfma_f32_16x16x32_bf16 v[24:27], v[240:243], v[160:163], v[24:27]
	v_mfma_f32_16x16x32_bf16 v[116:119], v[212:215], v[204:207], v[116:119]
	v_mfma_f32_16x16x32_bf16 v[112:115], v[240:243], v[204:207], v[112:115]
	v_mfma_f32_16x16x32_bf16 v[80:83], v[236:239], v[148:151], v[80:83]
	s_waitcnt lgkmcnt(0)
	v_mfma_f32_16x16x32_bf16 v[32:35], v[244:247], v[148:151], v[32:35]
	v_mfma_f32_16x16x32_bf16 v[76:79], v[236:239], v[156:159], v[76:79]
	v_mfma_f32_16x16x32_bf16 v[28:31], v[244:247], v[156:159], v[28:31]
	v_mfma_f32_16x16x32_bf16 v[72:75], v[236:239], v[164:167], v[72:75]
	v_mfma_f32_16x16x32_bf16 v[24:27], v[244:247], v[164:167], v[24:27]
	v_mfma_f32_16x16x32_bf16 v[116:119], v[236:239], v[208:211], v[116:119]
	v_mfma_f32_16x16x32_bf16 v[112:115], v[244:247], v[208:211], v[112:115]
	s_barrier
	ds_read_b128 v[144:147], v203 offset:49152
	ds_read_b128 v[148:151], v203 offset:50176
	ds_read_b128 v[152:155], v203 offset:51200
	ds_read_b128 v[156:159], v203 offset:52224
	ds_read_b128 v[160:163], v203 offset:53248
	ds_read_b128 v[164:167], v203 offset:54272
	ds_read_b128 v[204:207], v203 offset:55296
	ds_read_b128 v[208:211], v203 offset:56320
	s_add_u32 s48, s82, 0x4000
	s_addc_u32 s49, s83, 0
	s_mov_b32 m0, s40
	s_nop 0
	global_load_lds_dwordx4 v168, s[48:49]
	s_mov_b32 m0, s41
	s_nop 0
	global_load_lds_dwordx4 v188, s[48:49]
	s_barrier
; #define PG8_STAGE(bufoff, gbase, hoff, imm) do { _Pragma("unroll") for (int _i = 0; _i < 2; ++_i) { \
;         asm volatile("s_mov_b32 m0, %0\n\ts_nop 0\n\tglobal_load_lds_dwordx4 %1, %2" \
;             :: "s"(lds0 + (unsigned)((bufoff) + _i * 8192)), "v"(voff0), "s"((const char*)(gbase) + (size_t)(hoff) + (size_t)(_i * 8192)) : "memory"); } } while (0)
; #define PG8_LDA(dst, b, h) do { _Pragma("unroll") for (int m = 0; m < 4; ++m) _Pragma("unroll") for (int k = 0; k < 2; ++k) dst[m][k] = *(const LAS bf16x8*)(lds + PG8_SA(b, h) + aoff + m * 2048 + k * 1024); } while (0)
; #define PG8_LDB(dst, b, h) do { _Pragma("unroll") for (int n = 0; n < 2; ++n) _Pragma("unroll") for (int k = 0; k < 2; ++k) dst[n][k] = *(const LAS bf16x8*)(lds + PG8_SB(b, h) + boff + n * 2048 + k * 1024); } while (0)
; #define PG8_BAR __builtin_amdgcn_s_barrier()
; template <class Epi>
; __device__ __forceinline__ void gemm_phase(LAS unsigned char* lds, const Gemm g, const StaticOrder& S, const Epi& E) {
;     ...
;             const char* aT = cA + (size_t)t * KS;
;             const char* a2 = last ? nA : aT + 2 * KS; const char* b2 = last ? nB : cB + (size_t)(t + 2) * KS;
;             PG8_LDB(B0, 0, 0); PG8_SCHED; PG8_LDA(At, 0, 0); PG8_STAGE(PG8_SA(1, 1), aT + KS, hA, 0);
;             PG8_WAIT_L(8); PG8_BAR; PG8_WAIT_L(0); PG8_MMA(0, 0, At, B0); PG8_BAR; PG8_SCHED;
;             PG8_LDB(B1, 0, 1); PG8_STAGE(PG8_SB(0, 0), b2, 0, 0);
;             PG8_BAR; PG8_WAIT_L(0); PG8_MMA(0, 1, At, B1); PG8_BAR;
;             PG8_LDA(At, 0, 1); PG8_STAGE(PG8_SA(0, 0), a2, 0, 0);
;             PG8_BAR; PG8_WAIT_L(0); PG8_MMA(1, 0, At, B0); PG8_BAR; PG8_SCHED;
;             PG8_STAGE(PG8_SB(0, 1), b2, hB, 0);
;             PG8_WAIT_V(6); PG8_BAR; PG8_MMA(1, 1, At, B1); PG8_BAR;
;             PG8_LDB(B0, 1, 0); PG8_SCHED; PG8_LDA(At, 1, 0); PG8_STAGE(PG8_SA(0, 1), a2, hA, 0);
;             PG8_WAIT_L(8); PG8_BAR; PG8_WAIT_L(0); PG8_MMA(0, 0, At, B0); PG8_BAR; PG8_SCHED;
;             PG8_LDB(B1, 1, 1); PG8_STAGE(PG8_SB(1, 0), b2 + KS, 0, 0);
;             PG8_BAR; PG8_WAIT_L(0); PG8_MMA(0, 1, At, B1); PG8_BAR;
;             PG8_LDA(At, 1, 1); PG8_STAGE(PG8_SA(1, 0), a2 + KS, 0, 0);
;             PG8_BAR; PG8_WAIT_L(0); PG8_MMA(1, 0, At, B0); PG8_BAR; PG8_SCHED;
;             PG8_STAGE(PG8_SB(1, 1), b2 + KS, hB, 0);
;             PG8_WAIT_V(6); PG8_BAR; PG8_MMA(1, 1, At, B1); PG8_BAR;
	s_waitcnt lgkmcnt(7)
	v_mfma_f32_16x16x32_bf16 v[68:71], v[128:131], v[144:147], v[68:71]
	v_mfma_f32_16x16x32_bf16 v[20:23], v[136:139], v[144:147], v[20:23]
	s_waitcnt lgkmcnt(5)
	v_mfma_f32_16x16x32_bf16 v[64:67], v[128:131], v[152:155], v[64:67]
	v_mfma_f32_16x16x32_bf16 v[16:19], v[136:139], v[152:155], v[16:19]
	s_waitcnt lgkmcnt(3)
	v_mfma_f32_16x16x32_bf16 v[60:63], v[128:131], v[160:163], v[60:63]
	v_mfma_f32_16x16x32_bf16 v[12:15], v[136:139], v[160:163], v[12:15]
	s_waitcnt lgkmcnt(1)
	v_mfma_f32_16x16x32_bf16 v[108:111], v[128:131], v[204:207], v[108:111]
	v_mfma_f32_16x16x32_bf16 v[104:107], v[136:139], v[204:207], v[104:107]
	v_mfma_f32_16x16x32_bf16 v[68:71], v[132:135], v[148:151], v[68:71]
	v_mfma_f32_16x16x32_bf16 v[20:23], v[140:143], v[148:151], v[20:23]
	v_mfma_f32_16x16x32_bf16 v[64:67], v[132:135], v[156:159], v[64:67]
	v_mfma_f32_16x16x32_bf16 v[16:19], v[140:143], v[156:159], v[16:19]
	v_mfma_f32_16x16x32_bf16 v[60:63], v[132:135], v[164:167], v[60:63]
	v_mfma_f32_16x16x32_bf16 v[12:15], v[140:143], v[164:167], v[12:15]
	s_waitcnt lgkmcnt(0)
	v_mfma_f32_16x16x32_bf16 v[108:111], v[132:135], v[208:211], v[108:111]
	v_mfma_f32_16x16x32_bf16 v[104:107], v[140:143], v[208:211], v[104:107]
	s_barrier
	s_add_u32 s48, s78, 0x84000
	s_addc_u32 s49, s79, 0
	s_mov_b32 m0, s42
	s_nop 0
	global_load_lds_dwordx4 v168, s[48:49]
	s_mov_b32 m0, s43
	s_nop 0
	global_load_lds_dwordx4 v188, s[48:49]
	s_waitcnt vmcnt(10)
	s_barrier
	v_mfma_f32_16x16x32_bf16 v[56:59], v[212:215], v[144:147], v[56:59]
	v_mfma_f32_16x16x32_bf16 v[8:11], v[240:243], v[144:147], v[8:11]
	v_mfma_f32_16x16x32_bf16 v[52:55], v[212:215], v[152:155], v[52:55]
	v_mfma_f32_16x16x32_bf16 v[4:7], v[240:243], v[152:155], v[4:7]
	v_mfma_f32_16x16x32_bf16 v[48:51], v[212:215], v[160:163], v[48:51]
	v_mfma_f32_16x16x32_bf16 v[0:3], v[240:243], v[160:163], v[0:3]
	v_mfma_f32_16x16x32_bf16 v[100:103], v[212:215], v[204:207], v[100:103]
	v_mfma_f32_16x16x32_bf16 v[88:91], v[240:243], v[204:207], v[88:91]
	v_mfma_f32_16x16x32_bf16 v[56:59], v[236:239], v[148:151], v[56:59]
	v_mfma_f32_16x16x32_bf16 v[8:11], v[244:247], v[148:151], v[8:11]
	v_mfma_f32_16x16x32_bf16 v[52:55], v[236:239], v[156:159], v[52:55]
	v_mfma_f32_16x16x32_bf16 v[4:7], v[244:247], v[156:159], v[4:7]
	v_mfma_f32_16x16x32_bf16 v[48:51], v[236:239], v[164:167], v[48:51]
	v_mfma_f32_16x16x32_bf16 v[0:3], v[244:247], v[164:167], v[0:3]
	v_mfma_f32_16x16x32_bf16 v[100:103], v[236:239], v[208:211], v[100:103]
	v_mfma_f32_16x16x32_bf16 v[88:91], v[244:247], v[208:211], v[88:91]
	s_add_i32 s0, s0, 2
	s_add_u32 s9, s9, 0x8000
	s_addc_u32 s63, s63, 0
	s_cmp_gt_u32 s0, 29
	s_mov_b64 s[78:79], s[80:81]
	s_barrier
	s_branch .LBB0_507
.LBB0_506:
	ds_read_b128 v[128:131], v202
	ds_read_b128 v[132:135], v202 offset:1024
	ds_read_b128 v[136:139], v202 offset:2048
	ds_read_b128 v[140:143], v202 offset:3072
	s_add_u32 s80, s78, 0x8000
	s_addc_u32 s81, s79, 0
	s_and_b64 s[82:83], s[84:85], exec
	s_cselect_b32 s83, s51, s81
	s_cselect_b32 s82, s71, s80
	ds_read_b128 v[144:147], v203
	ds_read_b128 v[148:151], v203 offset:1024
	ds_read_b128 v[152:155], v203 offset:2048
	ds_read_b128 v[156:159], v203 offset:3072
	ds_read_b128 v[160:163], v203 offset:4096
	ds_read_b128 v[164:167], v203 offset:5120
	ds_read_b128 v[204:207], v203 offset:6144
	ds_read_b128 v[208:211], v203 offset:7168
	s_add_u32 s48, s78, 0x84000
	s_addc_u32 s49, s79, 0
	s_mov_b32 m0, s87
	s_nop 0
	global_load_lds_dwordx4 v168, s[48:49]
	s_mov_b32 m0, s96
	s_nop 0
	global_load_lds_dwordx4 v188, s[48:49]
	s_waitcnt lgkmcnt(8)
	s_waitcnt vmcnt(10)
	s_barrier
	s_waitcnt lgkmcnt(7)
	v_mfma_f32_16x16x32_bf16 v[96:99], v[128:131], v[144:147], v[96:99]
	v_mfma_f32_16x16x32_bf16 v[44:47], v[136:139], v[144:147], v[44:47]
	s_waitcnt lgkmcnt(5)
	v_mfma_f32_16x16x32_bf16 v[92:95], v[128:131], v[152:155], v[92:95]
	v_mfma_f32_16x16x32_bf16 v[40:43], v[136:139], v[152:155], v[40:43]
	s_waitcnt lgkmcnt(3)
	v_mfma_f32_16x16x32_bf16 v[84:87], v[128:131], v[160:163], v[84:87]
	v_mfma_f32_16x16x32_bf16 v[36:39], v[136:139], v[160:163], v[36:39]
	s_waitcnt lgkmcnt(1)
	v_mfma_f32_16x16x32_bf16 v[124:127], v[128:131], v[204:207], v[124:127]
	v_mfma_f32_16x16x32_bf16 v[120:123], v[136:139], v[204:207], v[120:123]
	v_mfma_f32_16x16x32_bf16 v[96:99], v[132:135], v[148:151], v[96:99]
	v_mfma_f32_16x16x32_bf16 v[44:47], v[140:143], v[148:151], v[44:47]
	v_mfma_f32_16x16x32_bf16 v[92:95], v[132:135], v[156:159], v[92:95]
	v_mfma_f32_16x16x32_bf16 v[40:43], v[140:143], v[156:159], v[40:43]
	v_mfma_f32_16x16x32_bf16 v[84:87], v[132:135], v[164:167], v[84:87]
	v_mfma_f32_16x16x32_bf16 v[36:39], v[140:143], v[164:167], v[36:39]
	s_waitcnt lgkmcnt(0)
	v_mfma_f32_16x16x32_bf16 v[124:127], v[132:135], v[208:211], v[124:127]
	v_mfma_f32_16x16x32_bf16 v[120:123], v[140:143], v[208:211], v[120:123]
	s_barrier
	ds_read_b128 v[212:215], v202 offset:16384
	ds_read_b128 v[236:239], v202 offset:17408
	ds_read_b128 v[240:243], v202 offset:18432
	ds_read_b128 v[244:247], v202 offset:19456
	s_and_b64 s[48:49], s[84:85], exec
	s_cselect_b32 s78, s62, s9
	s_cselect_b32 s79, s69, s63
	s_mov_b32 m0, s25
	s_nop 0
	global_load_lds_dwordx4 v168, s[78:79]
	s_mov_b32 m0, s26
	s_nop 0
	global_load_lds_dwordx4 v188, s[78:79]
	s_waitcnt vmcnt(10)
	s_barrier
; #define PG8_STAGE(bufoff, gbase, hoff, imm) do { _Pragma("unroll") for (int _i = 0; _i < 2; ++_i) { \
;         asm volatile("s_mov_b32 m0, %0\n\ts_nop 0\n\tglobal_load_lds_dwordx4 %1, %2" \
;             :: "s"(lds0 + (unsigned)((bufoff) + _i * 8192)), "v"(voff0), "s"((const char*)(gbase) + (size_t)(hoff) + (size_t)(_i * 8192)) : "memory"); } } while (0)
; #define PG8_LDA(dst, b, h) do { _Pragma("unroll") for (int m = 0; m < 4; ++m) _Pragma("unroll") for (int k = 0; k < 2; ++k) dst[m][k] = *(const LAS bf16x8*)(lds + PG8_SA(b, h) + aoff + m * 2048 + k * 1024); } while (0)
; #define PG8_LDB(dst, b, h) do { _Pragma("unroll") for (int n = 0; n < 2; ++n) _Pragma("unroll") for (int k = 0; k < 2; ++k) dst[n][k] = *(const LAS bf16x8*)(lds + PG8_SB(b, h) + boff + n * 2048 + k * 1024); } while (0)
; #define PG8_WAIT_V(n) asm volatile("s_waitcnt vmcnt(" #n ")" ::: "memory")
; #define PG8_WAIT_L(n) asm volatile("s_waitcnt lgkmcnt(" #n ")" ::: "memory")
; #define PG8_BAR __builtin_amdgcn_s_barrier()
; template <class Epi>
; __device__ __forceinline__ void gemm_phase(LAS unsigned char* lds, const Gemm g, const StaticOrder& S, const Epi& E) {
;     ...
;             PG8_LDB(B0, 0, 0); PG8_SCHED; PG8_LDA(At, 0, 0); PG8_STAGE(PG8_SA(1, 1), aT + KS, hA, 0);
;             PG8_WAIT_L(8); PG8_BAR; PG8_WAIT_L(0); PG8_MMA(0, 0, At, B0); PG8_BAR; PG8_SCHED;
;             PG8_LDB(B1, 0, 1); PG8_STAGE(PG8_SB(0, 0), b2, 0, 0);
;             PG8_BAR; PG8_WAIT_L(0); PG8_MMA(0, 1, At, B1); PG8_BAR;
;             PG8_LDA(At, 0, 1); PG8_STAGE(PG8_SA(0, 0), a2, 0, 0);
;             PG8_BAR; PG8_WAIT_L(0); PG8_MMA(1, 0, At, B0); PG8_BAR; PG8_SCHED;
;             PG8_STAGE(PG8_SB(0, 1), b2, hB, 0);
;             PG8_WAIT_V(6); PG8_BAR; PG8_MMA(1, 1, At, B1); PG8_BAR;
;             PG8_LDB(B0, 1, 0); PG8_SCHED; PG8_LDA(At, 1, 0); PG8_STAGE(PG8_SA(0, 1), a2, hA, 0);
;             PG8_WAIT_L(8); PG8_BAR; PG8_WAIT_L(0); PG8_MMA(0, 0, At, B0); PG8_BAR; PG8_SCHED;
;             PG8_LDB(B1, 1, 1); PG8_STAGE(PG8_SB(1, 0), b2 + KS, 0, 0);
;             PG8_BAR; PG8_WAIT_L(0); PG8_MMA(0, 1, At, B1); PG8_BAR;
;             PG8_LDA(At, 1, 1); PG8_STAGE(PG8_SA(1, 0), a2 + KS, 0, 0);
;             PG8_BAR; PG8_WAIT_L(0); PG8_MMA(1, 0, At, B0); PG8_BAR; PG8_SCHED;
;             PG8_STAGE(PG8_SB(1, 1), b2 + KS, hB, 0);
;             PG8_WAIT_V(6); PG8_BAR; PG8_MMA(1, 1, At, B1); PG8_BAR;
	s_waitcnt lgkmcnt(3)
	v_mfma_f32_16x16x32_bf16 v[80:83], v[212:215], v[144:147], v[80:83]
	s_waitcnt lgkmcnt(1)
	v_mfma_f32_16x16x32_bf16 v[32:35], v[240:243], v[144:147], v[32:35]
	v_mfma_f32_16x16x32_bf16 v[76:79], v[212:215], v[152:155], v[76:79]
	v_mfma_f32_16x16x32_bf16 v[28:31], v[240:243], v[152:155], v[28:31]
	v_mfma_f32_16x16x32_bf16 v[72:75], v[212:215], v[160:163], v[72:75]
	v_mfma_f32_16x16x32_bf16 v[24:27], v[240:243], v[160:163], v[24:27]
	v_mfma_f32_16x16x32_bf16 v[116:119], v[212:215], v[204:207], v[116:119]
	v_mfma_f32_16x16x32_bf16 v[112:115], v[240:243], v[204:207], v[112:115]
	v_mfma_f32_16x16x32_bf16 v[80:83], v[236:239], v[148:151], v[80:83]
	s_waitcnt lgkmcnt(0)
	v_mfma_f32_16x16x32_bf16 v[32:35], v[244:247], v[148:151], v[32:35]
	v_mfma_f32_16x16x32_bf16 v[76:79], v[236:239], v[156:159], v[76:79]
	v_mfma_f32_16x16x32_bf16 v[28:31], v[244:247], v[156:159], v[28:31]
	v_mfma_f32_16x16x32_bf16 v[72:75], v[236:239], v[164:167], v[72:75]
	v_mfma_f32_16x16x32_bf16 v[24:27], v[244:247], v[164:167], v[24:27]
	v_mfma_f32_16x16x32_bf16 v[116:119], v[236:239], v[208:211], v[116:119]
	v_mfma_f32_16x16x32_bf16 v[112:115], v[244:247], v[208:211], v[112:115]
	s_barrier
	ds_read_b128 v[144:147], v203 offset:16384
	ds_read_b128 v[148:151], v203 offset:17408
	ds_read_b128 v[152:155], v203 offset:18432
	ds_read_b128 v[156:159], v203 offset:19456
	ds_read_b128 v[160:163], v203 offset:20480
	ds_read_b128 v[164:167], v203 offset:21504
	ds_read_b128 v[204:207], v203 offset:22528
	ds_read_b128 v[208:211], v203 offset:23552
	s_mov_b32 m0, s24
	s_nop 0
	global_load_lds_dwordx4 v168, s[82:83]
	s_mov_b32 m0, s27
	s_nop 0
	global_load_lds_dwordx4 v188, s[82:83]
	s_barrier
	s_waitcnt lgkmcnt(7)
	v_mfma_f32_16x16x32_bf16 v[68:71], v[128:131], v[144:147], v[68:71]
	v_mfma_f32_16x16x32_bf16 v[20:23], v[136:139], v[144:147], v[20:23]
	s_waitcnt lgkmcnt(5)
	v_mfma_f32_16x16x32_bf16 v[64:67], v[128:131], v[152:155], v[64:67]
	v_mfma_f32_16x16x32_bf16 v[16:19], v[136:139], v[152:155], v[16:19]
	s_waitcnt lgkmcnt(3)
	v_mfma_f32_16x16x32_bf16 v[60:63], v[128:131], v[160:163], v[60:63]
	v_mfma_f32_16x16x32_bf16 v[12:15], v[136:139], v[160:163], v[12:15]
	s_waitcnt lgkmcnt(1)
	v_mfma_f32_16x16x32_bf16 v[108:111], v[128:131], v[204:207], v[108:111]
	v_mfma_f32_16x16x32_bf16 v[104:107], v[136:139], v[204:207], v[104:107]
	v_mfma_f32_16x16x32_bf16 v[68:71], v[132:135], v[148:151], v[68:71]
	v_mfma_f32_16x16x32_bf16 v[20:23], v[140:143], v[148:151], v[20:23]
	v_mfma_f32_16x16x32_bf16 v[64:67], v[132:135], v[156:159], v[64:67]
	v_mfma_f32_16x16x32_bf16 v[16:19], v[140:143], v[156:159], v[16:19]
	v_mfma_f32_16x16x32_bf16 v[60:63], v[132:135], v[164:167], v[60:63]
	v_mfma_f32_16x16x32_bf16 v[12:15], v[140:143], v[164:167], v[12:15]
	s_waitcnt lgkmcnt(0)
	v_mfma_f32_16x16x32_bf16 v[108:111], v[132:135], v[208:211], v[108:111]
	v_mfma_f32_16x16x32_bf16 v[104:107], v[140:143], v[208:211], v[104:107]
	s_barrier
	s_add_u32 s48, s78, 0x80000
	s_addc_u32 s49, s79, 0
	s_mov_b32 m0, s28
	s_nop 0
	global_load_lds_dwordx4 v168, s[48:49]
	s_mov_b32 m0, s29
	s_nop 0
	global_load_lds_dwordx4 v188, s[48:49]
	s_waitcnt vmcnt(10)
	s_barrier
	v_mfma_f32_16x16x32_bf16 v[56:59], v[212:215], v[144:147], v[56:59]
	v_mfma_f32_16x16x32_bf16 v[8:11], v[240:243], v[144:147], v[8:11]
	v_mfma_f32_16x16x32_bf16 v[52:55], v[212:215], v[152:155], v[52:55]
	v_mfma_f32_16x16x32_bf16 v[4:7], v[240:243], v[152:155], v[4:7]
	v_mfma_f32_16x16x32_bf16 v[48:51], v[212:215], v[160:163], v[48:51]
	v_mfma_f32_16x16x32_bf16 v[0:3], v[240:243], v[160:163], v[0:3]
	v_mfma_f32_16x16x32_bf16 v[100:103], v[212:215], v[204:207], v[100:103]
	v_mfma_f32_16x16x32_bf16 v[88:91], v[240:243], v[204:207], v[88:91]
	v_mfma_f32_16x16x32_bf16 v[56:59], v[236:239], v[148:151], v[56:59]
	v_mfma_f32_16x16x32_bf16 v[8:11], v[244:247], v[148:151], v[8:11]
	v_mfma_f32_16x16x32_bf16 v[52:55], v[236:239], v[156:159], v[52:55]
	v_mfma_f32_16x16x32_bf16 v[4:7], v[244:247], v[156:159], v[4:7]
	v_mfma_f32_16x16x32_bf16 v[48:51], v[236:239], v[164:167], v[48:51]
	v_mfma_f32_16x16x32_bf16 v[0:3], v[244:247], v[164:167], v[0:3]
	v_mfma_f32_16x16x32_bf16 v[100:103], v[236:239], v[208:211], v[100:103]
	v_mfma_f32_16x16x32_bf16 v[88:91], v[244:247], v[208:211], v[88:91]
	s_barrier
	ds_read_b128 v[128:131], v202 offset:32768
	ds_read_b128 v[132:135], v202 offset:33792
	ds_read_b128 v[136:139], v202 offset:34816
	ds_read_b128 v[140:143], v202 offset:35840
	ds_read_b128 v[144:147], v203 offset:32768
	ds_read_b128 v[148:151], v203 offset:33792
	ds_read_b128 v[152:155], v203 offset:34816
	ds_read_b128 v[156:159], v203 offset:35840
	ds_read_b128 v[160:163], v203 offset:36864
	ds_read_b128 v[164:167], v203 offset:37888
	ds_read_b128 v[204:207], v203 offset:38912
	ds_read_b128 v[208:211], v203 offset:39936
	s_add_u32 s48, s82, 0x80000
	s_addc_u32 s49, s83, 0
	s_mov_b32 m0, s30
	s_nop 0
	global_load_lds_dwordx4 v168, s[48:49]
	s_mov_b32 m0, s34
	s_nop 0
	global_load_lds_dwordx4 v188, s[48:49]
	s_waitcnt lgkmcnt(8)
	s_waitcnt vmcnt(10)
	s_barrier
; #define PG8_STAGE(bufoff, gbase, hoff, imm) do { _Pragma("unroll") for (int _i = 0; _i < 2; ++_i) { \
;         asm volatile("s_mov_b32 m0, %0\n\ts_nop 0\n\tglobal_load_lds_dwordx4 %1, %2" \
;             :: "s"(lds0 + (unsigned)((bufoff) + _i * 8192)), "v"(voff0), "s"((const char*)(gbase) + (size_t)(hoff) + (size_t)(_i * 8192)) : "memory"); } } while (0)
; #define PG8_LDA(dst, b, h) do { _Pragma("unroll") for (int m = 0; m < 4; ++m) _Pragma("unroll") for (int k = 0; k < 2; ++k) dst[m][k] = *(const LAS bf16x8*)(lds + PG8_SA(b, h) + aoff + m * 2048 + k * 1024); } while (0)
; #define PG8_LDB(dst, b, h) do { _Pragma("unroll") for (int n = 0; n < 2; ++n) _Pragma("unroll") for (int k = 0; k < 2; ++k) dst[n][k] = *(const LAS bf16x8*)(lds + PG8_SB(b, h) + boff + n * 2048 + k * 1024); } while (0)
; #define PG8_WAIT_V(n) asm volatile("s_waitcnt vmcnt(" #n ")" ::: "memory")
; #define PG8_WAIT_L(n) asm volatile("s_waitcnt lgkmcnt(" #n ")" ::: "memory")
; #define PG8_BAR __builtin_amdgcn_s_barrier()
; template <class Epi>
; __device__ __forceinline__ void gemm_phase(LAS unsigned char* lds, const Gemm g, const StaticOrder& S, const Epi& E) {
;     ...
;             PG8_LDB(B0, 0, 0); PG8_SCHED; PG8_LDA(At, 0, 0); PG8_STAGE(PG8_SA(1, 1), aT + KS, hA, 0);
;             PG8_WAIT_L(8); PG8_BAR; PG8_WAIT_L(0); PG8_MMA(0, 0, At, B0); PG8_BAR; PG8_SCHED;
;             PG8_LDB(B1, 0, 1); PG8_STAGE(PG8_SB(0, 0), b2, 0, 0);
;             PG8_BAR; PG8_WAIT_L(0); PG8_MMA(0, 1, At, B1); PG8_BAR;
;             PG8_LDA(At, 0, 1); PG8_STAGE(PG8_SA(0, 0), a2, 0, 0);
;             PG8_BAR; PG8_WAIT_L(0); PG8_MMA(1, 0, At, B0); PG8_BAR; PG8_SCHED;
;             PG8_STAGE(PG8_SB(0, 1), b2, hB, 0);
;             PG8_WAIT_V(6); PG8_BAR; PG8_MMA(1, 1, At, B1); PG8_BAR;
;             PG8_LDB(B0, 1, 0); PG8_SCHED; PG8_LDA(At, 1, 0); PG8_STAGE(PG8_SA(0, 1), a2, hA, 0);
;             PG8_WAIT_L(8); PG8_BAR; PG8_WAIT_L(0); PG8_MMA(0, 0, At, B0); PG8_BAR; PG8_SCHED;
;             PG8_LDB(B1, 1, 1); PG8_STAGE(PG8_SB(1, 0), b2 + KS, 0, 0);
;             PG8_BAR; PG8_WAIT_L(0); PG8_MMA(0, 1, At, B1); PG8_BAR;
;             PG8_LDA(At, 1, 1); PG8_STAGE(PG8_SA(1, 0), a2 + KS, 0, 0);
;             PG8_BAR; PG8_WAIT_L(0); PG8_MMA(1, 0, At, B0); PG8_BAR; PG8_SCHED;
;             PG8_STAGE(PG8_SB(1, 1), b2 + KS, hB, 0);
;             PG8_WAIT_V(6); PG8_BAR; PG8_MMA(1, 1, At, B1); PG8_BAR;
	s_waitcnt lgkmcnt(7)
	v_mfma_f32_16x16x32_bf16 v[96:99], v[128:131], v[144:147], v[96:99]
	v_mfma_f32_16x16x32_bf16 v[44:47], v[136:139], v[144:147], v[44:47]
	s_waitcnt lgkmcnt(5)
	v_mfma_f32_16x16x32_bf16 v[92:95], v[128:131], v[152:155], v[92:95]
	v_mfma_f32_16x16x32_bf16 v[40:43], v[136:139], v[152:155], v[40:43]
	s_waitcnt lgkmcnt(3)
	v_mfma_f32_16x16x32_bf16 v[84:87], v[128:131], v[160:163], v[84:87]
	v_mfma_f32_16x16x32_bf16 v[36:39], v[136:139], v[160:163], v[36:39]
	s_waitcnt lgkmcnt(1)
	v_mfma_f32_16x16x32_bf16 v[124:127], v[128:131], v[204:207], v[124:127]
	v_mfma_f32_16x16x32_bf16 v[120:123], v[136:139], v[204:207], v[120:123]
	v_mfma_f32_16x16x32_bf16 v[96:99], v[132:135], v[148:151], v[96:99]
	v_mfma_f32_16x16x32_bf16 v[44:47], v[140:143], v[148:151], v[44:47]
	v_mfma_f32_16x16x32_bf16 v[92:95], v[132:135], v[156:159], v[92:95]
	v_mfma_f32_16x16x32_bf16 v[40:43], v[140:143], v[156:159], v[40:43]
	v_mfma_f32_16x16x32_bf16 v[84:87], v[132:135], v[164:167], v[84:87]
	v_mfma_f32_16x16x32_bf16 v[36:39], v[140:143], v[164:167], v[36:39]
	s_waitcnt lgkmcnt(0)
	v_mfma_f32_16x16x32_bf16 v[124:127], v[132:135], v[208:211], v[124:127]
	v_mfma_f32_16x16x32_bf16 v[120:123], v[140:143], v[208:211], v[120:123]
	s_barrier
	ds_read_b128 v[212:215], v202 offset:49152
	ds_read_b128 v[236:239], v202 offset:50176
	ds_read_b128 v[240:243], v202 offset:51200
	ds_read_b128 v[244:247], v202 offset:52224
	s_add_u32 s48, s78, 0x4000
	s_addc_u32 s49, s79, 0
	s_mov_b32 m0, s38
	s_nop 0
	global_load_lds_dwordx4 v168, s[48:49]
	s_mov_b32 m0, s39
	s_nop 0
	global_load_lds_dwordx4 v188, s[48:49]
	s_waitcnt vmcnt(10)
	s_barrier
	s_waitcnt lgkmcnt(3)
	v_mfma_f32_16x16x32_bf16 v[80:83], v[212:215], v[144:147], v[80:83]
	s_waitcnt lgkmcnt(1)
	v_mfma_f32_16x16x32_bf16 v[32:35], v[240:243], v[144:147], v[32:35]
	v_mfma_f32_16x16x32_bf16 v[76:79], v[212:215], v[152:155], v[76:79]
	v_mfma_f32_16x16x32_bf16 v[28:31], v[240:243], v[152:155], v[28:31]
	v_mfma_f32_16x16x32_bf16 v[72:75], v[212:215], v[160:163], v[72:75]
	v_mfma_f32_16x16x32_bf16 v[24:27], v[240:243], v[160:163], v[24:27]
	v_mfma_f32_16x16x32_bf16 v[116:119], v[212:215], v[204:207], v[116:119]
	v_mfma_f32_16x16x32_bf16 v[112:115], v[240:243], v[204:207], v[112:115]
	v_mfma_f32_16x16x32_bf16 v[80:83], v[236:239], v[148:151], v[80:83]
	s_waitcnt lgkmcnt(0)
	v_mfma_f32_16x16x32_bf16 v[32:35], v[244:247], v[148:151], v[32:35]
	v_mfma_f32_16x16x32_bf16 v[76:79], v[236:239], v[156:159], v[76:79]
	v_mfma_f32_16x16x32_bf16 v[28:31], v[244:247], v[156:159], v[28:31]
	v_mfma_f32_16x16x32_bf16 v[72:75], v[236:239], v[164:167], v[72:75]
	v_mfma_f32_16x16x32_bf16 v[24:27], v[244:247], v[164:167], v[24:27]
	v_mfma_f32_16x16x32_bf16 v[116:119], v[236:239], v[208:211], v[116:119]
	v_mfma_f32_16x16x32_bf16 v[112:115], v[244:247], v[208:211], v[112:115]
	s_barrier
	ds_read_b128 v[144:147], v203 offset:49152
	ds_read_b128 v[148:151], v203 offset:50176
	ds_read_b128 v[152:155], v203 offset:51200
	ds_read_b128 v[156:159], v203 offset:52224
	ds_read_b128 v[160:163], v203 offset:53248
	ds_read_b128 v[164:167], v203 offset:54272
	ds_read_b128 v[204:207], v203 offset:55296
	ds_read_b128 v[208:211], v203 offset:56320
	s_add_u32 s48, s82, 0x4000
	s_addc_u32 s49, s83, 0
	s_mov_b32 m0, s40
	s_nop 0
	global_load_lds_dwordx4 v168, s[48:49]
	s_mov_b32 m0, s41
	s_nop 0
	global_load_lds_dwordx4 v188, s[48:49]
	s_barrier
	s_waitcnt lgkmcnt(7)
	v_mfma_f32_16x16x32_bf16 v[68:71], v[128:131], v[144:147], v[68:71]
	v_mfma_f32_16x16x32_bf16 v[20:23], v[136:139], v[144:147], v[20:23]
	s_waitcnt lgkmcnt(5)
	v_mfma_f32_16x16x32_bf16 v[64:67], v[128:131], v[152:155], v[64:67]
	v_mfma_f32_16x16x32_bf16 v[16:19], v[136:139], v[152:155], v[16:19]
	s_waitcnt lgkmcnt(3)
	v_mfma_f32_16x16x32_bf16 v[60:63], v[128:131], v[160:163], v[60:63]
	v_mfma_f32_16x16x32_bf16 v[12:15], v[136:139], v[160:163], v[12:15]
	s_waitcnt lgkmcnt(1)
	v_mfma_f32_16x16x32_bf16 v[108:111], v[128:131], v[204:207], v[108:111]
	v_mfma_f32_16x16x32_bf16 v[104:107], v[136:139], v[204:207], v[104:107]
	v_mfma_f32_16x16x32_bf16 v[68:71], v[132:135], v[148:151], v[68:71]
	v_mfma_f32_16x16x32_bf16 v[20:23], v[140:143], v[148:151], v[20:23]
	v_mfma_f32_16x16x32_bf16 v[64:67], v[132:135], v[156:159], v[64:67]
	v_mfma_f32_16x16x32_bf16 v[16:19], v[140:143], v[156:159], v[16:19]
	v_mfma_f32_16x16x32_bf16 v[60:63], v[132:135], v[164:167], v[60:63]
	v_mfma_f32_16x16x32_bf16 v[12:15], v[140:143], v[164:167], v[12:15]
	s_waitcnt lgkmcnt(0)
	v_mfma_f32_16x16x32_bf16 v[108:111], v[132:135], v[208:211], v[108:111]
	v_mfma_f32_16x16x32_bf16 v[104:107], v[140:143], v[208:211], v[104:107]
	s_barrier
	s_add_u32 s48, s78, 0x84000
	s_addc_u32 s49, s79, 0
	s_mov_b32 m0, s42
	s_nop 0
	global_load_lds_dwordx4 v168, s[48:49]
	s_mov_b32 m0, s43
	s_nop 0
	global_load_lds_dwordx4 v188, s[48:49]
	s_waitcnt vmcnt(10)
	s_barrier
	v_mfma_f32_16x16x32_bf16 v[56:59], v[212:215], v[144:147], v[56:59]
	v_mfma_f32_16x16x32_bf16 v[8:11], v[240:243], v[144:147], v[8:11]
	v_mfma_f32_16x16x32_bf16 v[52:55], v[212:215], v[152:155], v[52:55]
	v_mfma_f32_16x16x32_bf16 v[4:7], v[240:243], v[152:155], v[4:7]
	v_mfma_f32_16x16x32_bf16 v[48:51], v[212:215], v[160:163], v[48:51]
	v_mfma_f32_16x16x32_bf16 v[0:3], v[240:243], v[160:163], v[0:3]
	v_mfma_f32_16x16x32_bf16 v[100:103], v[212:215], v[204:207], v[100:103]
	v_mfma_f32_16x16x32_bf16 v[88:91], v[240:243], v[204:207], v[88:91]
	v_mfma_f32_16x16x32_bf16 v[56:59], v[236:239], v[148:151], v[56:59]
	v_mfma_f32_16x16x32_bf16 v[8:11], v[244:247], v[148:151], v[8:11]
	v_mfma_f32_16x16x32_bf16 v[52:55], v[236:239], v[156:159], v[52:55]
	v_mfma_f32_16x16x32_bf16 v[4:7], v[244:247], v[156:159], v[4:7]
	v_mfma_f32_16x16x32_bf16 v[48:51], v[236:239], v[164:167], v[48:51]
	v_mfma_f32_16x16x32_bf16 v[0:3], v[244:247], v[164:167], v[0:3]
	v_mfma_f32_16x16x32_bf16 v[100:103], v[236:239], v[208:211], v[100:103]
	v_mfma_f32_16x16x32_bf16 v[88:91], v[244:247], v[208:211], v[88:91]
	s_add_i32 s0, s0, 2
	s_add_u32 s9, s9, 0x8000
	s_addc_u32 s63, s63, 0
	s_cmp_gt_u32 s0, 29
	s_mov_b64 s[78:79], s[80:81]
	s_barrier
	s_cbranch_scc1 .LBB0_509

; #define PG8_STAGE(bufoff, gbase, hoff, imm) do { _Pragma("unroll") for (int _i = 0; _i < 2; ++_i) { \
;         asm volatile("s_mov_b32 m0, %0\n\ts_nop 0\n\tglobal_load_lds_dwordx4 %1, %2" \
;             :: "s"(lds0 + (unsigned)((bufoff) + _i * 8192)), "v"(voff0), "s"((const char*)(gbase) + (size_t)(hoff) + (size_t)(_i * 8192)) : "memory"); } } while (0)
; #define PG8_LDA(dst, b, h) do { _Pragma("unroll") for (int m = 0; m < 4; ++m) _Pragma("unroll") for (int k = 0; k < 2; ++k) dst[m][k] = *(const LAS bf16x8*)(lds + PG8_SA(b, h) + aoff + m * 2048 + k * 1024); } while (0)
; #define PG8_LDB(dst, b, h) do { _Pragma("unroll") for (int n = 0; n < 2; ++n) _Pragma("unroll") for (int k = 0; k < 2; ++k) dst[n][k] = *(const LAS bf16x8*)(lds + PG8_SB(b, h) + boff + n * 2048 + k * 1024); } while (0)
; #define PG8_MMA(ai, bj, At, Bt) do { __builtin_amdgcn_s_setprio(1); _Pragma("unroll") for (int m = 0; m < 4; ++m) _Pragma("unroll") for (int n = 0; n < 2; ++n) _Pragma("unroll") for (int k = 0; k < 2; ++k) \
;         acc[ai][bj][m][n] = __builtin_amdgcn_mfma_f32_16x16x32_bf16(Bt[n][k], At[m][k], acc[ai][bj][m][n], 0, 0, 0); __builtin_amdgcn_s_setprio(0); } while (0)
; #define PG8_WAIT_L(n) asm volatile("s_waitcnt lgkmcnt(" #n ")" ::: "memory")
; #define PG8_BAR __builtin_amdgcn_s_barrier()
; template <class Epi>
; __device__ __forceinline__ void gemm_phase(LAS unsigned char* lds, const Gemm g, const StaticOrder& S, const Epi& E) {
;     ...
;         const bool has_next = S.next(ui + 1, nxt);
;         const char* nA = has_next ? (const char*)g.A + (size_t)nxt.pm * tstepA + (size_t)(nxt.pn >> g.gshift) * g.gstride : cA;
;         const char* nB = has_next ? (const char*)g.Bt + (size_t)nxt.pn * tstepB : cB;
;         for (int t = 0; t < nt; t += 2) {
;             const bool last = (t == nt - 2);
;             if (last) E.pre(cur, wid, lane, (unsigned)(size_t)(lds + STAGE_BYTES));
;             const char* aT = cA + (size_t)t * KS;
;             const char* a2 = last ? nA : aT + 2 * KS; const char* b2 = last ? nB : cB + (size_t)(t + 2) * KS;
;             PG8_LDB(B0, 0, 0); PG8_SCHED; PG8_LDA(At, 0, 0); PG8_STAGE(PG8_SA(1, 1), aT + KS, hA, 0);
;             PG8_WAIT_L(8); PG8_BAR; PG8_WAIT_L(0); PG8_MMA(0, 0, At, B0); PG8_BAR; PG8_SCHED;
;             PG8_LDB(B1, 0, 1); PG8_STAGE(PG8_SB(0, 0), b2, 0, 0);
;             PG8_BAR; PG8_WAIT_L(0); PG8_MMA(0, 1, At, B1); PG8_BAR;
.LBB0_737:
	s_ashr_i32 s71, s70, 31
	v_cmp_lt_i64_e32 vcc, s[8:9], v[198:199]
	s_lshl_b64 s[8:9], s[70:71], 20
	s_add_u32 s72, s26, s8
	s_addc_u32 s73, s27, s9
	s_and_b64 s[8:9], vcc, exec
	s_cselect_b32 s50, s73, s77
	s_cselect_b32 s51, s72, s76
	s_ashr_i32 s69, s68, 31
	s_lshl_b64 s[8:9], s[68:69], 20
	s_add_u32 s74, s84, s8
	s_addc_u32 s75, s85, s9
	s_and_b64 s[8:9], vcc, exec
	s_cselect_b32 s69, s75, s79
	s_cselect_b32 s0, s74, s78
	s_lshl_b32 s8, s1, 7
	s_ashr_i32 s9, s8, 31
	s_lshl_b64 s[10:11], s[8:9], 2
	s_add_u32 s10, s96, s10
	s_addc_u32 s11, s30, s11
	s_add_u32 s1, s78, 0x8000
	s_addc_u32 s9, s79, 0
	s_mov_b32 s71, -2
	ds_read_b128 v[128:131], v177
	ds_read_b128 v[132:135], v177 offset:1024
	ds_read_b128 v[136:139], v177 offset:2048
	ds_read_b128 v[140:143], v177 offset:3072
	v_add_u32_e32 v188, 0x2000, v152
	s_mov_b64 s[82:83], 0
	s_add_u32 s78, s76, 0x8000
	s_addc_u32 s79, s77, 0
	s_and_b64 s[48:49], s[82:83], exec
	s_cselect_b32 s81, s50, s79
	s_cselect_b32 s80, s51, s78
	ds_read_b128 v[144:147], v178
	ds_read_b128 v[148:151], v178 offset:1024
	ds_read_b128 v[184:187], v178 offset:2048
	ds_read_b128 v[200:203], v178 offset:3072
	ds_read_b128 v[204:207], v178 offset:4096
	ds_read_b128 v[208:211], v178 offset:5120
	ds_read_b128 v[212:215], v178 offset:6144
	ds_read_b128 v[236:239], v178 offset:7168
	s_waitcnt lgkmcnt(8)
	s_waitcnt vmcnt(10)
	s_barrier
	s_waitcnt lgkmcnt(7)
	v_mfma_f32_16x16x32_bf16 v[116:119], v[128:131], v[144:147], 0
	v_mfma_f32_16x16x32_bf16 v[80:83], v[136:139], v[144:147], 0
	s_waitcnt lgkmcnt(5)
	v_mfma_f32_16x16x32_bf16 v[88:91], v[128:131], v[184:187], 0
	v_mfma_f32_16x16x32_bf16 v[84:87], v[136:139], v[184:187], 0
	s_waitcnt lgkmcnt(3)
	v_mfma_f32_16x16x32_bf16 v[120:123], v[128:131], v[204:207], 0
	v_mfma_f32_16x16x32_bf16 v[92:95], v[136:139], v[204:207], 0
	s_waitcnt lgkmcnt(1)
	v_mfma_f32_16x16x32_bf16 v[124:127], v[128:131], v[212:215], 0
	v_mfma_f32_16x16x32_bf16 v[96:99], v[136:139], v[212:215], 0
	v_mfma_f32_16x16x32_bf16 v[116:119], v[132:135], v[148:151], v[116:119]
	v_mfma_f32_16x16x32_bf16 v[80:83], v[140:143], v[148:151], v[80:83]
	v_mfma_f32_16x16x32_bf16 v[88:91], v[132:135], v[200:203], v[88:91]
	v_mfma_f32_16x16x32_bf16 v[84:87], v[140:143], v[200:203], v[84:87]
	v_mfma_f32_16x16x32_bf16 v[120:123], v[132:135], v[208:211], v[120:123]
	v_mfma_f32_16x16x32_bf16 v[92:95], v[140:143], v[208:211], v[92:95]
	s_waitcnt lgkmcnt(0)
	v_mfma_f32_16x16x32_bf16 v[124:127], v[132:135], v[236:239], v[124:127]
	v_mfma_f32_16x16x32_bf16 v[96:99], v[140:143], v[236:239], v[96:99]
	s_barrier
	ds_read_b128 v[240:243], v177 offset:16384
	ds_read_b128 v[244:247], v177 offset:17408
	ds_read_b128 v[248:251], v177 offset:18432
	ds_read_b128 v[230:233], v177 offset:19456
	s_and_b64 s[48:49], s[82:83], exec
	s_cselect_b32 s76, s0, s1
	s_cselect_b32 s77, s69, s9
	s_mov_b32 m0, s28
	s_nop 0
	global_load_lds_dwordx4 v152, s[76:77]
	s_mov_b32 m0, s29
	s_nop 0
	global_load_lds_dwordx4 v188, s[76:77]
	s_waitcnt vmcnt(10)
	s_barrier
	s_waitcnt lgkmcnt(3)
	v_mfma_f32_16x16x32_bf16 v[48:51], v[240:243], v[144:147], 0
	s_waitcnt lgkmcnt(1)
	v_mfma_f32_16x16x32_bf16 v[16:19], v[248:251], v[144:147], 0
	v_mfma_f32_16x16x32_bf16 v[52:55], v[240:243], v[184:187], 0
	v_mfma_f32_16x16x32_bf16 v[20:23], v[248:251], v[184:187], 0
	v_mfma_f32_16x16x32_bf16 v[56:59], v[240:243], v[204:207], 0
	v_mfma_f32_16x16x32_bf16 v[24:27], v[248:251], v[204:207], 0
	v_mfma_f32_16x16x32_bf16 v[60:63], v[240:243], v[212:215], 0
	v_mfma_f32_16x16x32_bf16 v[28:31], v[248:251], v[212:215], 0
	v_mfma_f32_16x16x32_bf16 v[48:51], v[244:247], v[148:151], v[48:51]
	s_waitcnt lgkmcnt(0)
	v_mfma_f32_16x16x32_bf16 v[16:19], v[230:233], v[148:151], v[16:19]
	v_mfma_f32_16x16x32_bf16 v[52:55], v[244:247], v[200:203], v[52:55]
	v_mfma_f32_16x16x32_bf16 v[20:23], v[230:233], v[200:203], v[20:23]
	v_mfma_f32_16x16x32_bf16 v[56:59], v[244:247], v[208:211], v[56:59]
	v_mfma_f32_16x16x32_bf16 v[24:27], v[230:233], v[208:211], v[24:27]
	v_mfma_f32_16x16x32_bf16 v[60:63], v[244:247], v[236:239], v[60:63]
	v_mfma_f32_16x16x32_bf16 v[28:31], v[230:233], v[236:239], v[28:31]
	s_barrier
	ds_read_b128 v[144:147], v178 offset:16384
	ds_read_b128 v[148:151], v178 offset:17408
	ds_read_b128 v[184:187], v178 offset:18432
	ds_read_b128 v[200:203], v178 offset:19456
	ds_read_b128 v[204:207], v178 offset:20480
	ds_read_b128 v[208:211], v178 offset:21504
	ds_read_b128 v[212:215], v178 offset:22528
	ds_read_b128 v[236:239], v178 offset:23552
	s_mov_b32 m0, s89
	s_nop 0
	global_load_lds_dwordx4 v152, s[80:81]
	s_mov_b32 m0, s40
	s_nop 0
	global_load_lds_dwordx4 v188, s[80:81]
	s_waitcnt vmcnt(10)
	s_barrier
	s_waitcnt lgkmcnt(7)
	v_mfma_f32_16x16x32_bf16 v[100:103], v[128:131], v[144:147], 0
	v_mfma_f32_16x16x32_bf16 v[64:67], v[136:139], v[144:147], 0
	s_waitcnt lgkmcnt(5)
	v_mfma_f32_16x16x32_bf16 v[104:107], v[128:131], v[184:187], 0
	v_mfma_f32_16x16x32_bf16 v[68:71], v[136:139], v[184:187], 0
	s_waitcnt lgkmcnt(3)
	v_mfma_f32_16x16x32_bf16 v[108:111], v[128:131], v[204:207], 0
	v_mfma_f32_16x16x32_bf16 v[72:75], v[136:139], v[204:207], 0
	s_waitcnt lgkmcnt(1)
	v_mfma_f32_16x16x32_bf16 v[112:115], v[128:131], v[212:215], 0
	v_mfma_f32_16x16x32_bf16 v[76:79], v[136:139], v[212:215], 0
	v_mfma_f32_16x16x32_bf16 v[100:103], v[132:135], v[148:151], v[100:103]
	v_mfma_f32_16x16x32_bf16 v[64:67], v[140:143], v[148:151], v[64:67]
	v_mfma_f32_16x16x32_bf16 v[104:107], v[132:135], v[200:203], v[104:107]
	v_mfma_f32_16x16x32_bf16 v[68:71], v[140:143], v[200:203], v[68:71]
	v_mfma_f32_16x16x32_bf16 v[108:111], v[132:135], v[208:211], v[108:111]
	v_mfma_f32_16x16x32_bf16 v[72:75], v[140:143], v[208:211], v[72:75]
	s_waitcnt lgkmcnt(0)
	v_mfma_f32_16x16x32_bf16 v[112:115], v[132:135], v[236:239], v[112:115]
	v_mfma_f32_16x16x32_bf16 v[76:79], v[140:143], v[236:239], v[76:79]
	s_barrier
; #define PG8_STAGE(bufoff, gbase, hoff, imm) do { _Pragma("unroll") for (int _i = 0; _i < 2; ++_i) { \
;         asm volatile("s_mov_b32 m0, %0\n\ts_nop 0\n\tglobal_load_lds_dwordx4 %1, %2" \
;             :: "s"(lds0 + (unsigned)((bufoff) + _i * 8192)), "v"(voff0), "s"((const char*)(gbase) + (size_t)(hoff) + (size_t)(_i * 8192)) : "memory"); } } while (0)
; #define PG8_LDA(dst, b, h) do { _Pragma("unroll") for (int m = 0; m < 4; ++m) _Pragma("unroll") for (int k = 0; k < 2; ++k) dst[m][k] = *(const LAS bf16x8*)(lds + PG8_SA(b, h) + aoff + m * 2048 + k * 1024); } while (0)
; #define PG8_LDB(dst, b, h) do { _Pragma("unroll") for (int n = 0; n < 2; ++n) _Pragma("unroll") for (int k = 0; k < 2; ++k) dst[n][k] = *(const LAS bf16x8*)(lds + PG8_SB(b, h) + boff + n * 2048 + k * 1024); } while (0)
; #define PG8_MMA(ai, bj, At, Bt) do { __builtin_amdgcn_s_setprio(1); _Pragma("unroll") for (int m = 0; m < 4; ++m) _Pragma("unroll") for (int n = 0; n < 2; ++n) _Pragma("unroll") for (int k = 0; k < 2; ++k) \
;         acc[ai][bj][m][n] = __builtin_amdgcn_mfma_f32_16x16x32_bf16(Bt[n][k], At[m][k], acc[ai][bj][m][n], 0, 0, 0); __builtin_amdgcn_s_setprio(0); } while (0)
; #define PG8_WAIT_V(n) asm volatile("s_waitcnt vmcnt(" #n ")" ::: "memory")
; #define PG8_WAIT_L(n) asm volatile("s_waitcnt lgkmcnt(" #n ")" ::: "memory")
; template <class Epi>
; __device__ __forceinline__ void gemm_phase(LAS unsigned char* lds, const Gemm g, const StaticOrder& S, const Epi& E) {
;     ...
;             PG8_LDA(At, 0, 1); PG8_STAGE(PG8_SA(0, 0), a2, 0, 0);
;             PG8_BAR; PG8_WAIT_L(0); PG8_MMA(1, 0, At, B0); PG8_BAR; PG8_SCHED;
;             PG8_STAGE(PG8_SB(0, 1), b2, hB, 0);
;             PG8_WAIT_V(6); PG8_BAR; PG8_MMA(1, 1, At, B1); PG8_BAR;
;             PG8_LDB(B0, 1, 0); PG8_SCHED; PG8_LDA(At, 1, 0); PG8_STAGE(PG8_SA(0, 1), a2, hA, 0);
;             PG8_WAIT_L(8); PG8_BAR; PG8_WAIT_L(0); PG8_MMA(0, 0, At, B0); PG8_BAR; PG8_SCHED;
;             PG8_LDB(B1, 1, 1); PG8_STAGE(PG8_SB(1, 0), b2 + KS, 0, 0);
;             PG8_BAR; PG8_WAIT_L(0); PG8_MMA(0, 1, At, B1); PG8_BAR;
;             PG8_LDA(At, 1, 1); PG8_STAGE(PG8_SA(1, 0), a2 + KS, 0, 0);
;             PG8_BAR; PG8_WAIT_L(0); PG8_MMA(1, 0, At, B0); PG8_BAR; PG8_SCHED;
;             PG8_STAGE(PG8_SB(1, 1), b2 + KS, hB, 0);
;             PG8_WAIT_V(6); PG8_BAR; PG8_MMA(1, 1, At, B1); PG8_BAR;
	ds_read_b128 v[128:131], v177 offset:32768
	ds_read_b128 v[132:135], v177 offset:33792
	ds_read_b128 v[136:139], v177 offset:34816
	ds_read_b128 v[140:143], v177 offset:35840
	s_add_u32 s48, s76, 0x80000
	s_addc_u32 s49, s77, 0
	s_mov_b32 m0, s41
	s_nop 0
	global_load_lds_dwordx4 v152, s[48:49]
	s_mov_b32 m0, s42
	s_nop 0
	global_load_lds_dwordx4 v188, s[48:49]
	s_add_u32 s48, s80, 0x80000
	s_addc_u32 s49, s81, 0
	s_mov_b32 m0, s43
	s_nop 0
	global_load_lds_dwordx4 v152, s[48:49]
	s_mov_b32 m0, s92
	s_nop 0
	global_load_lds_dwordx4 v188, s[48:49]
	s_waitcnt vmcnt(12)
	s_barrier
	v_mfma_f32_16x16x32_bf16 v[32:35], v[240:243], v[144:147], 0
	v_mfma_f32_16x16x32_bf16 v[0:3], v[248:251], v[144:147], 0
	v_mfma_f32_16x16x32_bf16 v[36:39], v[240:243], v[184:187], 0
	v_mfma_f32_16x16x32_bf16 v[4:7], v[248:251], v[184:187], 0
	v_mfma_f32_16x16x32_bf16 v[40:43], v[240:243], v[204:207], 0
	v_mfma_f32_16x16x32_bf16 v[8:11], v[248:251], v[204:207], 0
	v_mfma_f32_16x16x32_bf16 v[44:47], v[240:243], v[212:215], 0
	v_mfma_f32_16x16x32_bf16 v[12:15], v[248:251], v[212:215], 0
	v_mfma_f32_16x16x32_bf16 v[32:35], v[244:247], v[148:151], v[32:35]
	v_mfma_f32_16x16x32_bf16 v[0:3], v[230:233], v[148:151], v[0:3]
	v_mfma_f32_16x16x32_bf16 v[36:39], v[244:247], v[200:203], v[36:39]
	v_mfma_f32_16x16x32_bf16 v[4:7], v[230:233], v[200:203], v[4:7]
	v_mfma_f32_16x16x32_bf16 v[40:43], v[244:247], v[208:211], v[40:43]
	v_mfma_f32_16x16x32_bf16 v[8:11], v[230:233], v[208:211], v[8:11]
	v_mfma_f32_16x16x32_bf16 v[44:47], v[244:247], v[236:239], v[44:47]
	v_mfma_f32_16x16x32_bf16 v[12:15], v[230:233], v[236:239], v[12:15]
	s_barrier
	ds_read_b128 v[144:147], v178 offset:32768
	ds_read_b128 v[148:151], v178 offset:33792
	ds_read_b128 v[184:187], v178 offset:34816
	ds_read_b128 v[200:203], v178 offset:35840
	ds_read_b128 v[204:207], v178 offset:36864
	ds_read_b128 v[208:211], v178 offset:37888
	ds_read_b128 v[212:215], v178 offset:38912
	ds_read_b128 v[230:233], v178 offset:39936
	s_waitcnt lgkmcnt(8)
	s_waitcnt vmcnt(10)
	s_barrier
	s_waitcnt lgkmcnt(7)
	v_mfma_f32_16x16x32_bf16 v[116:119], v[128:131], v[144:147], v[116:119]
	v_mfma_f32_16x16x32_bf16 v[80:83], v[136:139], v[144:147], v[80:83]
	s_waitcnt lgkmcnt(5)
	v_mfma_f32_16x16x32_bf16 v[88:91], v[128:131], v[184:187], v[88:91]
	v_mfma_f32_16x16x32_bf16 v[84:87], v[136:139], v[184:187], v[84:87]
	s_waitcnt lgkmcnt(3)
	v_mfma_f32_16x16x32_bf16 v[120:123], v[128:131], v[204:207], v[120:123]
	v_mfma_f32_16x16x32_bf16 v[92:95], v[136:139], v[204:207], v[92:95]
	s_waitcnt lgkmcnt(1)
	v_mfma_f32_16x16x32_bf16 v[124:127], v[128:131], v[212:215], v[124:127]
	v_mfma_f32_16x16x32_bf16 v[96:99], v[136:139], v[212:215], v[96:99]
	v_mfma_f32_16x16x32_bf16 v[116:119], v[132:135], v[148:151], v[116:119]
	v_mfma_f32_16x16x32_bf16 v[80:83], v[140:143], v[148:151], v[80:83]
	v_mfma_f32_16x16x32_bf16 v[88:91], v[132:135], v[200:203], v[88:91]
	v_mfma_f32_16x16x32_bf16 v[84:87], v[140:143], v[200:203], v[84:87]
	v_mfma_f32_16x16x32_bf16 v[120:123], v[132:135], v[208:211], v[120:123]
	v_mfma_f32_16x16x32_bf16 v[92:95], v[140:143], v[208:211], v[92:95]
	s_waitcnt lgkmcnt(0)
	v_mfma_f32_16x16x32_bf16 v[124:127], v[132:135], v[230:233], v[124:127]
	v_mfma_f32_16x16x32_bf16 v[96:99], v[140:143], v[230:233], v[96:99]
	s_barrier
	ds_read_b128 v[236:239], v177 offset:49152
	ds_read_b128 v[240:243], v177 offset:50176
	ds_read_b128 v[244:247], v177 offset:51200
	ds_read_b128 v[248:251], v177 offset:52224
	s_add_u32 s48, s76, 0x4000
	s_addc_u32 s49, s77, 0
	s_mov_b32 m0, s16
	s_nop 0
	global_load_lds_dwordx4 v152, s[48:49]
	s_mov_b32 m0, s17
	s_nop 0
	global_load_lds_dwordx4 v188, s[48:49]
	s_waitcnt vmcnt(10)
	s_barrier
	s_waitcnt lgkmcnt(3)
	v_mfma_f32_16x16x32_bf16 v[48:51], v[236:239], v[144:147], v[48:51]
	s_waitcnt lgkmcnt(1)
	v_mfma_f32_16x16x32_bf16 v[16:19], v[244:247], v[144:147], v[16:19]
	v_mfma_f32_16x16x32_bf16 v[52:55], v[236:239], v[184:187], v[52:55]
	v_mfma_f32_16x16x32_bf16 v[20:23], v[244:247], v[184:187], v[20:23]
	v_mfma_f32_16x16x32_bf16 v[56:59], v[236:239], v[204:207], v[56:59]
	v_mfma_f32_16x16x32_bf16 v[24:27], v[244:247], v[204:207], v[24:27]
	v_mfma_f32_16x16x32_bf16 v[60:63], v[236:239], v[212:215], v[60:63]
	v_mfma_f32_16x16x32_bf16 v[28:31], v[244:247], v[212:215], v[28:31]
	v_mfma_f32_16x16x32_bf16 v[48:51], v[240:243], v[148:151], v[48:51]
	s_waitcnt lgkmcnt(0)
	v_mfma_f32_16x16x32_bf16 v[16:19], v[248:251], v[148:151], v[16:19]
	v_mfma_f32_16x16x32_bf16 v[52:55], v[240:243], v[200:203], v[52:55]
	v_mfma_f32_16x16x32_bf16 v[20:23], v[248:251], v[200:203], v[20:23]
	v_mfma_f32_16x16x32_bf16 v[56:59], v[240:243], v[208:211], v[56:59]
	v_mfma_f32_16x16x32_bf16 v[24:27], v[248:251], v[208:211], v[24:27]
	v_mfma_f32_16x16x32_bf16 v[60:63], v[240:243], v[230:233], v[60:63]
	v_mfma_f32_16x16x32_bf16 v[28:31], v[248:251], v[230:233], v[28:31]
	s_barrier
	ds_read_b128 v[144:147], v178 offset:49152
	ds_read_b128 v[148:151], v178 offset:50176
	ds_read_b128 v[184:187], v178 offset:51200
	ds_read_b128 v[200:203], v178 offset:52224
	ds_read_b128 v[204:207], v178 offset:53248
	ds_read_b128 v[208:211], v178 offset:54272
	ds_read_b128 v[212:215], v178 offset:55296
	ds_read_b128 v[230:233], v178 offset:56320
	s_add_u32 s48, s80, 0x4000
	s_addc_u32 s49, s81, 0
	s_mov_b32 m0, s24
	s_nop 0
	global_load_lds_dwordx4 v152, s[48:49]
	s_mov_b32 m0, s37
	s_nop 0
	global_load_lds_dwordx4 v188, s[48:49]
	s_waitcnt vmcnt(10)
	s_barrier
; #define PG8_STAGE(bufoff, gbase, hoff, imm) do { _Pragma("unroll") for (int _i = 0; _i < 2; ++_i) { \
;         asm volatile("s_mov_b32 m0, %0\n\ts_nop 0\n\tglobal_load_lds_dwordx4 %1, %2" \
;             :: "s"(lds0 + (unsigned)((bufoff) + _i * 8192)), "v"(voff0), "s"((const char*)(gbase) + (size_t)(hoff) + (size_t)(_i * 8192)) : "memory"); } } while (0)
; #define PG8_LDA(dst, b, h) do { _Pragma("unroll") for (int m = 0; m < 4; ++m) _Pragma("unroll") for (int k = 0; k < 2; ++k) dst[m][k] = *(const LAS bf16x8*)(lds + PG8_SA(b, h) + aoff + m * 2048 + k * 1024); } while (0)
; #define PG8_WAIT_V(n) asm volatile("s_waitcnt vmcnt(" #n ")" ::: "memory")
; template <class Epi>
; __device__ __forceinline__ void gemm_phase(LAS unsigned char* lds, const Gemm g, const StaticOrder& S, const Epi& E) {
;     ...
;         for (int t = 0; t < nt; t += 2) {
;             const bool last = (t == nt - 2);
;             if (last) E.pre(cur, wid, lane, (unsigned)(size_t)(lds + STAGE_BYTES));
;             const char* aT = cA + (size_t)t * KS;
;             const char* a2 = last ? nA : aT + 2 * KS; const char* b2 = last ? nB : cB + (size_t)(t + 2) * KS;
;             PG8_LDB(B0, 0, 0); PG8_SCHED; PG8_LDA(At, 0, 0); PG8_STAGE(PG8_SA(1, 1), aT + KS, hA, 0);
;             PG8_WAIT_L(8); PG8_BAR; PG8_WAIT_L(0); PG8_MMA(0, 0, At, B0); PG8_BAR; PG8_SCHED;
;             PG8_LDB(B1, 0, 1); PG8_STAGE(PG8_SB(0, 0), b2, 0, 0);
;             PG8_BAR; PG8_WAIT_L(0); PG8_MMA(0, 1, At, B1); PG8_BAR;
;             PG8_LDA(At, 0, 1); PG8_STAGE(PG8_SA(0, 0), a2, 0, 0);
;             PG8_BAR; PG8_WAIT_L(0); PG8_MMA(1, 0, At, B0); PG8_BAR; PG8_SCHED;
;             PG8_STAGE(PG8_SB(0, 1), b2, hB, 0);
;             PG8_WAIT_V(6); PG8_BAR; PG8_MMA(1, 1, At, B1); PG8_BAR;
;             PG8_LDB(B0, 1, 0); PG8_SCHED; PG8_LDA(At, 1, 0); PG8_STAGE(PG8_SA(0, 1), a2, hA, 0);
;             PG8_WAIT_L(8); PG8_BAR; PG8_WAIT_L(0); PG8_MMA(0, 0, At, B0); PG8_BAR; PG8_SCHED;
;             PG8_LDB(B1, 1, 1); PG8_STAGE(PG8_SB(1, 0), b2 + KS, 0, 0);
;             PG8_BAR; PG8_WAIT_L(0); PG8_MMA(0, 1, At, B1); PG8_BAR;
;             PG8_LDA(At, 1, 1); PG8_STAGE(PG8_SA(1, 0), a2 + KS, 0, 0);
;             PG8_BAR; PG8_WAIT_L(0); PG8_MMA(1, 0, At, B0); PG8_BAR; PG8_SCHED;
;             PG8_STAGE(PG8_SB(1, 1), b2 + KS, hB, 0);
;             PG8_WAIT_V(6); PG8_BAR; PG8_MMA(1, 1, At, B1); PG8_BAR;
	s_waitcnt lgkmcnt(7)
	v_mfma_f32_16x16x32_bf16 v[100:103], v[128:131], v[144:147], v[100:103]
	v_mfma_f32_16x16x32_bf16 v[64:67], v[136:139], v[144:147], v[64:67]
	s_waitcnt lgkmcnt(5)
	v_mfma_f32_16x16x32_bf16 v[104:107], v[128:131], v[184:187], v[104:107]
	v_mfma_f32_16x16x32_bf16 v[68:71], v[136:139], v[184:187], v[68:71]
	s_waitcnt lgkmcnt(3)
	v_mfma_f32_16x16x32_bf16 v[108:111], v[128:131], v[204:207], v[108:111]
	v_mfma_f32_16x16x32_bf16 v[72:75], v[136:139], v[204:207], v[72:75]
	s_waitcnt lgkmcnt(1)
	v_mfma_f32_16x16x32_bf16 v[112:115], v[128:131], v[212:215], v[112:115]
	v_mfma_f32_16x16x32_bf16 v[76:79], v[136:139], v[212:215], v[76:79]
	v_mfma_f32_16x16x32_bf16 v[100:103], v[132:135], v[148:151], v[100:103]
	v_mfma_f32_16x16x32_bf16 v[64:67], v[140:143], v[148:151], v[64:67]
	v_mfma_f32_16x16x32_bf16 v[104:107], v[132:135], v[200:203], v[104:107]
	v_mfma_f32_16x16x32_bf16 v[68:71], v[140:143], v[200:203], v[68:71]
	v_mfma_f32_16x16x32_bf16 v[108:111], v[132:135], v[208:211], v[108:111]
	v_mfma_f32_16x16x32_bf16 v[72:75], v[140:143], v[208:211], v[72:75]
	s_waitcnt lgkmcnt(0)
	v_mfma_f32_16x16x32_bf16 v[112:115], v[132:135], v[230:233], v[112:115]
	v_mfma_f32_16x16x32_bf16 v[76:79], v[140:143], v[230:233], v[76:79]
	s_barrier
	ds_read_b128 v[128:131], v177
	ds_read_b128 v[132:135], v177 offset:1024
	ds_read_b128 v[136:139], v177 offset:2048
	ds_read_b128 v[140:143], v177 offset:3072
	s_add_u32 s48, s76, 0x84000
	s_addc_u32 s49, s77, 0
	s_mov_b32 m0, s97
	s_nop 0
	global_load_lds_dwordx4 v152, s[48:49]
	s_mov_b32 m0, s38
	s_nop 0
	global_load_lds_dwordx4 v188, s[48:49]
	s_add_u32 s48, s80, 0x84000
	s_addc_u32 s49, s81, 0
	s_mov_b32 m0, s34
	s_nop 0
	global_load_lds_dwordx4 v152, s[48:49]
	s_mov_b32 m0, s25
	s_nop 0
	global_load_lds_dwordx4 v188, s[48:49]
	s_waitcnt vmcnt(12)
	s_barrier
	v_mfma_f32_16x16x32_bf16 v[32:35], v[236:239], v[144:147], v[32:35]
	v_mfma_f32_16x16x32_bf16 v[0:3], v[244:247], v[144:147], v[0:3]
	v_mfma_f32_16x16x32_bf16 v[36:39], v[236:239], v[184:187], v[36:39]
	v_mfma_f32_16x16x32_bf16 v[4:7], v[244:247], v[184:187], v[4:7]
	v_mfma_f32_16x16x32_bf16 v[40:43], v[236:239], v[204:207], v[40:43]
	v_mfma_f32_16x16x32_bf16 v[8:11], v[244:247], v[204:207], v[8:11]
	v_mfma_f32_16x16x32_bf16 v[44:47], v[236:239], v[212:215], v[44:47]
	v_mfma_f32_16x16x32_bf16 v[12:15], v[244:247], v[212:215], v[12:15]
	v_mfma_f32_16x16x32_bf16 v[32:35], v[240:243], v[148:151], v[32:35]
	v_mfma_f32_16x16x32_bf16 v[0:3], v[248:251], v[148:151], v[0:3]
	v_mfma_f32_16x16x32_bf16 v[36:39], v[240:243], v[200:203], v[36:39]
	v_mfma_f32_16x16x32_bf16 v[4:7], v[248:251], v[200:203], v[4:7]
	v_mfma_f32_16x16x32_bf16 v[40:43], v[240:243], v[208:211], v[40:43]
	v_mfma_f32_16x16x32_bf16 v[8:11], v[248:251], v[208:211], v[8:11]
	v_mfma_f32_16x16x32_bf16 v[44:47], v[240:243], v[230:233], v[44:47]
	v_mfma_f32_16x16x32_bf16 v[12:15], v[248:251], v[230:233], v[12:15]
	s_add_i32 s71, s71, 2
	s_add_u32 s1, s1, 0x8000
	s_addc_u32 s9, s9, 0
	s_cmp_gt_u32 s71, 29
	s_mov_b64 s[76:77], s[78:79]
	s_barrier
	s_branch .LBB0_739
.LBB0_738:
	s_add_u32 s78, s76, 0x8000
	s_addc_u32 s79, s77, 0
	s_and_b64 s[48:49], s[82:83], exec
	s_cselect_b32 s81, s50, s79
	s_cselect_b32 s80, s51, s78
	ds_read_b128 v[144:147], v178
	ds_read_b128 v[148:151], v178 offset:1024
	ds_read_b128 v[184:187], v178 offset:2048
	ds_read_b128 v[200:203], v178 offset:3072
	ds_read_b128 v[204:207], v178 offset:4096
	ds_read_b128 v[208:211], v178 offset:5120
	ds_read_b128 v[212:215], v178 offset:6144
	ds_read_b128 v[236:239], v178 offset:7168
	s_waitcnt lgkmcnt(8)
	s_waitcnt vmcnt(10)
	s_barrier
	s_waitcnt lgkmcnt(7)
	v_mfma_f32_16x16x32_bf16 v[116:119], v[128:131], v[144:147], v[116:119]
	v_mfma_f32_16x16x32_bf16 v[80:83], v[136:139], v[144:147], v[80:83]
	s_waitcnt lgkmcnt(5)
	v_mfma_f32_16x16x32_bf16 v[88:91], v[128:131], v[184:187], v[88:91]
	v_mfma_f32_16x16x32_bf16 v[84:87], v[136:139], v[184:187], v[84:87]
	s_waitcnt lgkmcnt(3)
	v_mfma_f32_16x16x32_bf16 v[120:123], v[128:131], v[204:207], v[120:123]
	v_mfma_f32_16x16x32_bf16 v[92:95], v[136:139], v[204:207], v[92:95]
	s_waitcnt lgkmcnt(1)
	v_mfma_f32_16x16x32_bf16 v[124:127], v[128:131], v[212:215], v[124:127]
	v_mfma_f32_16x16x32_bf16 v[96:99], v[136:139], v[212:215], v[96:99]
	v_mfma_f32_16x16x32_bf16 v[116:119], v[132:135], v[148:151], v[116:119]
	v_mfma_f32_16x16x32_bf16 v[80:83], v[140:143], v[148:151], v[80:83]
	v_mfma_f32_16x16x32_bf16 v[88:91], v[132:135], v[200:203], v[88:91]
	v_mfma_f32_16x16x32_bf16 v[84:87], v[140:143], v[200:203], v[84:87]
	v_mfma_f32_16x16x32_bf16 v[120:123], v[132:135], v[208:211], v[120:123]
	v_mfma_f32_16x16x32_bf16 v[92:95], v[140:143], v[208:211], v[92:95]
	s_waitcnt lgkmcnt(0)
	v_mfma_f32_16x16x32_bf16 v[124:127], v[132:135], v[236:239], v[124:127]
	v_mfma_f32_16x16x32_bf16 v[96:99], v[140:143], v[236:239], v[96:99]
	s_barrier
	ds_read_b128 v[240:243], v177 offset:16384
	ds_read_b128 v[244:247], v177 offset:17408
	ds_read_b128 v[248:251], v177 offset:18432
	ds_read_b128 v[230:233], v177 offset:19456
	s_and_b64 s[48:49], s[82:83], exec
	s_cselect_b32 s76, s0, s1
	s_cselect_b32 s77, s69, s9
	s_mov_b32 m0, s28
	s_nop 0
	global_load_lds_dwordx4 v152, s[76:77]
	s_mov_b32 m0, s29
	s_nop 0
	global_load_lds_dwordx4 v188, s[76:77]
	s_waitcnt vmcnt(10)
	s_barrier
; #define PG8_STAGE(bufoff, gbase, hoff, imm) do { _Pragma("unroll") for (int _i = 0; _i < 2; ++_i) { \
;         asm volatile("s_mov_b32 m0, %0\n\ts_nop 0\n\tglobal_load_lds_dwordx4 %1, %2" \
;             :: "s"(lds0 + (unsigned)((bufoff) + _i * 8192)), "v"(voff0), "s"((const char*)(gbase) + (size_t)(hoff) + (size_t)(_i * 8192)) : "memory"); } } while (0)
; #define PG8_LDA(dst, b, h) do { _Pragma("unroll") for (int m = 0; m < 4; ++m) _Pragma("unroll") for (int k = 0; k < 2; ++k) dst[m][k] = *(const LAS bf16x8*)(lds + PG8_SA(b, h) + aoff + m * 2048 + k * 1024); } while (0)
; #define PG8_LDB(dst, b, h) do { _Pragma("unroll") for (int n = 0; n < 2; ++n) _Pragma("unroll") for (int k = 0; k < 2; ++k) dst[n][k] = *(const LAS bf16x8*)(lds + PG8_SB(b, h) + boff + n * 2048 + k * 1024); } while (0)
; #define PG8_WAIT_V(n) asm volatile("s_waitcnt vmcnt(" #n ")" ::: "memory")
; #define PG8_WAIT_L(n) asm volatile("s_waitcnt lgkmcnt(" #n ")" ::: "memory")
; #define PG8_BAR __builtin_amdgcn_s_barrier()
; template <class Epi>
; __device__ __forceinline__ void gemm_phase(LAS unsigned char* lds, const Gemm g, const StaticOrder& S, const Epi& E) {
;     ...
;             PG8_LDB(B0, 0, 0); PG8_SCHED; PG8_LDA(At, 0, 0); PG8_STAGE(PG8_SA(1, 1), aT + KS, hA, 0);
;             PG8_WAIT_L(8); PG8_BAR; PG8_WAIT_L(0); PG8_MMA(0, 0, At, B0); PG8_BAR; PG8_SCHED;
;             PG8_LDB(B1, 0, 1); PG8_STAGE(PG8_SB(0, 0), b2, 0, 0);
;             PG8_BAR; PG8_WAIT_L(0); PG8_MMA(0, 1, At, B1); PG8_BAR;
;             PG8_LDA(At, 0, 1); PG8_STAGE(PG8_SA(0, 0), a2, 0, 0);
;             PG8_BAR; PG8_WAIT_L(0); PG8_MMA(1, 0, At, B0); PG8_BAR; PG8_SCHED;
;             PG8_STAGE(PG8_SB(0, 1), b2, hB, 0);
;             PG8_WAIT_V(6); PG8_BAR; PG8_MMA(1, 1, At, B1); PG8_BAR;
;             PG8_LDB(B0, 1, 0); PG8_SCHED; PG8_LDA(At, 1, 0); PG8_STAGE(PG8_SA(0, 1), a2, hA, 0);
;             PG8_WAIT_L(8); PG8_BAR; PG8_WAIT_L(0); PG8_MMA(0, 0, At, B0); PG8_BAR; PG8_SCHED;
;             PG8_LDB(B1, 1, 1); PG8_STAGE(PG8_SB(1, 0), b2 + KS, 0, 0);
;             PG8_BAR; PG8_WAIT_L(0); PG8_MMA(0, 1, At, B1); PG8_BAR;
;             PG8_LDA(At, 1, 1); PG8_STAGE(PG8_SA(1, 0), a2 + KS, 0, 0);
;             PG8_BAR; PG8_WAIT_L(0); PG8_MMA(1, 0, At, B0); PG8_BAR; PG8_SCHED;
;             PG8_STAGE(PG8_SB(1, 1), b2 + KS, hB, 0);
;             PG8_WAIT_V(6); PG8_BAR; PG8_MMA(1, 1, At, B1); PG8_BAR;
	s_waitcnt lgkmcnt(3)
	v_mfma_f32_16x16x32_bf16 v[48:51], v[240:243], v[144:147], v[48:51]
	s_waitcnt lgkmcnt(1)
	v_mfma_f32_16x16x32_bf16 v[16:19], v[248:251], v[144:147], v[16:19]
	v_mfma_f32_16x16x32_bf16 v[52:55], v[240:243], v[184:187], v[52:55]
	v_mfma_f32_16x16x32_bf16 v[20:23], v[248:251], v[184:187], v[20:23]
	v_mfma_f32_16x16x32_bf16 v[56:59], v[240:243], v[204:207], v[56:59]
	v_mfma_f32_16x16x32_bf16 v[24:27], v[248:251], v[204:207], v[24:27]
	v_mfma_f32_16x16x32_bf16 v[60:63], v[240:243], v[212:215], v[60:63]
	v_mfma_f32_16x16x32_bf16 v[28:31], v[248:251], v[212:215], v[28:31]
	v_mfma_f32_16x16x32_bf16 v[48:51], v[244:247], v[148:151], v[48:51]
	s_waitcnt lgkmcnt(0)
	v_mfma_f32_16x16x32_bf16 v[16:19], v[230:233], v[148:151], v[16:19]
	v_mfma_f32_16x16x32_bf16 v[52:55], v[244:247], v[200:203], v[52:55]
	v_mfma_f32_16x16x32_bf16 v[20:23], v[230:233], v[200:203], v[20:23]
	v_mfma_f32_16x16x32_bf16 v[56:59], v[244:247], v[208:211], v[56:59]
	v_mfma_f32_16x16x32_bf16 v[24:27], v[230:233], v[208:211], v[24:27]
	v_mfma_f32_16x16x32_bf16 v[60:63], v[244:247], v[236:239], v[60:63]
	v_mfma_f32_16x16x32_bf16 v[28:31], v[230:233], v[236:239], v[28:31]
	s_barrier
	ds_read_b128 v[144:147], v178 offset:16384
	ds_read_b128 v[148:151], v178 offset:17408
	ds_read_b128 v[184:187], v178 offset:18432
	ds_read_b128 v[200:203], v178 offset:19456
	ds_read_b128 v[204:207], v178 offset:20480
	ds_read_b128 v[208:211], v178 offset:21504
	ds_read_b128 v[212:215], v178 offset:22528
	ds_read_b128 v[236:239], v178 offset:23552
	s_mov_b32 m0, s89
	s_nop 0
	global_load_lds_dwordx4 v152, s[80:81]
	s_mov_b32 m0, s40
	s_nop 0
	global_load_lds_dwordx4 v188, s[80:81]
	s_waitcnt vmcnt(10)
	s_barrier
	s_waitcnt lgkmcnt(7)
	v_mfma_f32_16x16x32_bf16 v[100:103], v[128:131], v[144:147], v[100:103]
	v_mfma_f32_16x16x32_bf16 v[64:67], v[136:139], v[144:147], v[64:67]
	s_waitcnt lgkmcnt(5)
	v_mfma_f32_16x16x32_bf16 v[104:107], v[128:131], v[184:187], v[104:107]
	v_mfma_f32_16x16x32_bf16 v[68:71], v[136:139], v[184:187], v[68:71]
	s_waitcnt lgkmcnt(3)
	v_mfma_f32_16x16x32_bf16 v[108:111], v[128:131], v[204:207], v[108:111]
	v_mfma_f32_16x16x32_bf16 v[72:75], v[136:139], v[204:207], v[72:75]
	s_waitcnt lgkmcnt(1)
	v_mfma_f32_16x16x32_bf16 v[112:115], v[128:131], v[212:215], v[112:115]
	v_mfma_f32_16x16x32_bf16 v[76:79], v[136:139], v[212:215], v[76:79]
	v_mfma_f32_16x16x32_bf16 v[100:103], v[132:135], v[148:151], v[100:103]
	v_mfma_f32_16x16x32_bf16 v[64:67], v[140:143], v[148:151], v[64:67]
	v_mfma_f32_16x16x32_bf16 v[104:107], v[132:135], v[200:203], v[104:107]
	v_mfma_f32_16x16x32_bf16 v[68:71], v[140:143], v[200:203], v[68:71]
	v_mfma_f32_16x16x32_bf16 v[108:111], v[132:135], v[208:211], v[108:111]
	v_mfma_f32_16x16x32_bf16 v[72:75], v[140:143], v[208:211], v[72:75]
	s_waitcnt lgkmcnt(0)
	v_mfma_f32_16x16x32_bf16 v[112:115], v[132:135], v[236:239], v[112:115]
	v_mfma_f32_16x16x32_bf16 v[76:79], v[140:143], v[236:239], v[76:79]
	s_barrier
	ds_read_b128 v[128:131], v177 offset:32768
	ds_read_b128 v[132:135], v177 offset:33792
	ds_read_b128 v[136:139], v177 offset:34816
	ds_read_b128 v[140:143], v177 offset:35840
	s_add_u32 s48, s76, 0x80000
	s_addc_u32 s49, s77, 0
	s_mov_b32 m0, s41
	s_nop 0
	global_load_lds_dwordx4 v152, s[48:49]
	s_mov_b32 m0, s42
	s_nop 0
	global_load_lds_dwordx4 v188, s[48:49]
	s_add_u32 s48, s80, 0x80000
	s_addc_u32 s49, s81, 0
	s_mov_b32 m0, s43
	s_nop 0
	global_load_lds_dwordx4 v152, s[48:49]
	s_mov_b32 m0, s92
	s_nop 0
	global_load_lds_dwordx4 v188, s[48:49]
	s_waitcnt vmcnt(12)
	s_barrier
	v_mfma_f32_16x16x32_bf16 v[32:35], v[240:243], v[144:147], v[32:35]
	v_mfma_f32_16x16x32_bf16 v[0:3], v[248:251], v[144:147], v[0:3]
	v_mfma_f32_16x16x32_bf16 v[36:39], v[240:243], v[184:187], v[36:39]
	v_mfma_f32_16x16x32_bf16 v[4:7], v[248:251], v[184:187], v[4:7]
	v_mfma_f32_16x16x32_bf16 v[40:43], v[240:243], v[204:207], v[40:43]
	v_mfma_f32_16x16x32_bf16 v[8:11], v[248:251], v[204:207], v[8:11]
	v_mfma_f32_16x16x32_bf16 v[44:47], v[240:243], v[212:215], v[44:47]
	v_mfma_f32_16x16x32_bf16 v[12:15], v[248:251], v[212:215], v[12:15]
	v_mfma_f32_16x16x32_bf16 v[32:35], v[244:247], v[148:151], v[32:35]
	v_mfma_f32_16x16x32_bf16 v[0:3], v[230:233], v[148:151], v[0:3]
	v_mfma_f32_16x16x32_bf16 v[36:39], v[244:247], v[200:203], v[36:39]
	v_mfma_f32_16x16x32_bf16 v[4:7], v[230:233], v[200:203], v[4:7]
	v_mfma_f32_16x16x32_bf16 v[40:43], v[244:247], v[208:211], v[40:43]
	v_mfma_f32_16x16x32_bf16 v[8:11], v[230:233], v[208:211], v[8:11]
	v_mfma_f32_16x16x32_bf16 v[44:47], v[244:247], v[236:239], v[44:47]
	v_mfma_f32_16x16x32_bf16 v[12:15], v[230:233], v[236:239], v[12:15]
	s_barrier
	ds_read_b128 v[144:147], v178 offset:32768
	ds_read_b128 v[148:151], v178 offset:33792
	ds_read_b128 v[184:187], v178 offset:34816
	ds_read_b128 v[200:203], v178 offset:35840
	ds_read_b128 v[204:207], v178 offset:36864
	ds_read_b128 v[208:211], v178 offset:37888
	ds_read_b128 v[212:215], v178 offset:38912
	ds_read_b128 v[230:233], v178 offset:39936
	s_waitcnt lgkmcnt(8)
	s_waitcnt vmcnt(10)
	s_barrier
; #define PG8_STAGE(bufoff, gbase, hoff, imm) do { _Pragma("unroll") for (int _i = 0; _i < 2; ++_i) { \
;         asm volatile("s_mov_b32 m0, %0\n\ts_nop 0\n\tglobal_load_lds_dwordx4 %1, %2" \
;             :: "s"(lds0 + (unsigned)((bufoff) + _i * 8192)), "v"(voff0), "s"((const char*)(gbase) + (size_t)(hoff) + (size_t)(_i * 8192)) : "memory"); } } while (0)
; #define PG8_LDA(dst, b, h) do { _Pragma("unroll") for (int m = 0; m < 4; ++m) _Pragma("unroll") for (int k = 0; k < 2; ++k) dst[m][k] = *(const LAS bf16x8*)(lds + PG8_SA(b, h) + aoff + m * 2048 + k * 1024); } while (0)
; #define PG8_LDB(dst, b, h) do { _Pragma("unroll") for (int n = 0; n < 2; ++n) _Pragma("unroll") for (int k = 0; k < 2; ++k) dst[n][k] = *(const LAS bf16x8*)(lds + PG8_SB(b, h) + boff + n * 2048 + k * 1024); } while (0)
; #define PG8_WAIT_V(n) asm volatile("s_waitcnt vmcnt(" #n ")" ::: "memory")
; #define PG8_WAIT_L(n) asm volatile("s_waitcnt lgkmcnt(" #n ")" ::: "memory")
; #define PG8_BAR __builtin_amdgcn_s_barrier()
; template <class Epi>
; __device__ __forceinline__ void gemm_phase(LAS unsigned char* lds, const Gemm g, const StaticOrder& S, const Epi& E) {
;     ...
;             PG8_LDB(B0, 0, 0); PG8_SCHED; PG8_LDA(At, 0, 0); PG8_STAGE(PG8_SA(1, 1), aT + KS, hA, 0);
;             PG8_WAIT_L(8); PG8_BAR; PG8_WAIT_L(0); PG8_MMA(0, 0, At, B0); PG8_BAR; PG8_SCHED;
;             PG8_LDB(B1, 0, 1); PG8_STAGE(PG8_SB(0, 0), b2, 0, 0);
;             PG8_BAR; PG8_WAIT_L(0); PG8_MMA(0, 1, At, B1); PG8_BAR;
;             PG8_LDA(At, 0, 1); PG8_STAGE(PG8_SA(0, 0), a2, 0, 0);
;             PG8_BAR; PG8_WAIT_L(0); PG8_MMA(1, 0, At, B0); PG8_BAR; PG8_SCHED;
;             PG8_STAGE(PG8_SB(0, 1), b2, hB, 0);
;             PG8_WAIT_V(6); PG8_BAR; PG8_MMA(1, 1, At, B1); PG8_BAR;
;             PG8_LDB(B0, 1, 0); PG8_SCHED; PG8_LDA(At, 1, 0); PG8_STAGE(PG8_SA(0, 1), a2, hA, 0);
;             PG8_WAIT_L(8); PG8_BAR; PG8_WAIT_L(0); PG8_MMA(0, 0, At, B0); PG8_BAR; PG8_SCHED;
;             PG8_LDB(B1, 1, 1); PG8_STAGE(PG8_SB(1, 0), b2 + KS, 0, 0);
;             PG8_BAR; PG8_WAIT_L(0); PG8_MMA(0, 1, At, B1); PG8_BAR;
;             PG8_LDA(At, 1, 1); PG8_STAGE(PG8_SA(1, 0), a2 + KS, 0, 0);
;             PG8_BAR; PG8_WAIT_L(0); PG8_MMA(1, 0, At, B0); PG8_BAR; PG8_SCHED;
;             PG8_STAGE(PG8_SB(1, 1), b2 + KS, hB, 0);
;             PG8_WAIT_V(6); PG8_BAR; PG8_MMA(1, 1, At, B1); PG8_BAR;
	s_waitcnt lgkmcnt(7)
	v_mfma_f32_16x16x32_bf16 v[116:119], v[128:131], v[144:147], v[116:119]
	v_mfma_f32_16x16x32_bf16 v[80:83], v[136:139], v[144:147], v[80:83]
	s_waitcnt lgkmcnt(5)
	v_mfma_f32_16x16x32_bf16 v[88:91], v[128:131], v[184:187], v[88:91]
	v_mfma_f32_16x16x32_bf16 v[84:87], v[136:139], v[184:187], v[84:87]
	s_waitcnt lgkmcnt(3)
	v_mfma_f32_16x16x32_bf16 v[120:123], v[128:131], v[204:207], v[120:123]
	v_mfma_f32_16x16x32_bf16 v[92:95], v[136:139], v[204:207], v[92:95]
	s_waitcnt lgkmcnt(1)
	v_mfma_f32_16x16x32_bf16 v[124:127], v[128:131], v[212:215], v[124:127]
	v_mfma_f32_16x16x32_bf16 v[96:99], v[136:139], v[212:215], v[96:99]
	v_mfma_f32_16x16x32_bf16 v[116:119], v[132:135], v[148:151], v[116:119]
	v_mfma_f32_16x16x32_bf16 v[80:83], v[140:143], v[148:151], v[80:83]
	v_mfma_f32_16x16x32_bf16 v[88:91], v[132:135], v[200:203], v[88:91]
	v_mfma_f32_16x16x32_bf16 v[84:87], v[140:143], v[200:203], v[84:87]
	v_mfma_f32_16x16x32_bf16 v[120:123], v[132:135], v[208:211], v[120:123]
	v_mfma_f32_16x16x32_bf16 v[92:95], v[140:143], v[208:211], v[92:95]
	s_waitcnt lgkmcnt(0)
	v_mfma_f32_16x16x32_bf16 v[124:127], v[132:135], v[230:233], v[124:127]
	v_mfma_f32_16x16x32_bf16 v[96:99], v[140:143], v[230:233], v[96:99]
	s_barrier
	ds_read_b128 v[236:239], v177 offset:49152
	ds_read_b128 v[240:243], v177 offset:50176
	ds_read_b128 v[244:247], v177 offset:51200
	ds_read_b128 v[248:251], v177 offset:52224
	s_add_u32 s48, s76, 0x4000
	s_addc_u32 s49, s77, 0
	s_mov_b32 m0, s16
	s_nop 0
	global_load_lds_dwordx4 v152, s[48:49]
	s_mov_b32 m0, s17
	s_nop 0
	global_load_lds_dwordx4 v188, s[48:49]
	s_waitcnt vmcnt(10)
	s_barrier
	s_waitcnt lgkmcnt(3)
	v_mfma_f32_16x16x32_bf16 v[48:51], v[236:239], v[144:147], v[48:51]
	s_waitcnt lgkmcnt(1)
	v_mfma_f32_16x16x32_bf16 v[16:19], v[244:247], v[144:147], v[16:19]
	v_mfma_f32_16x16x32_bf16 v[52:55], v[236:239], v[184:187], v[52:55]
	v_mfma_f32_16x16x32_bf16 v[20:23], v[244:247], v[184:187], v[20:23]
	v_mfma_f32_16x16x32_bf16 v[56:59], v[236:239], v[204:207], v[56:59]
	v_mfma_f32_16x16x32_bf16 v[24:27], v[244:247], v[204:207], v[24:27]
	v_mfma_f32_16x16x32_bf16 v[60:63], v[236:239], v[212:215], v[60:63]
	v_mfma_f32_16x16x32_bf16 v[28:31], v[244:247], v[212:215], v[28:31]
	v_mfma_f32_16x16x32_bf16 v[48:51], v[240:243], v[148:151], v[48:51]
	s_waitcnt lgkmcnt(0)
	v_mfma_f32_16x16x32_bf16 v[16:19], v[248:251], v[148:151], v[16:19]
	v_mfma_f32_16x16x32_bf16 v[52:55], v[240:243], v[200:203], v[52:55]
	v_mfma_f32_16x16x32_bf16 v[20:23], v[248:251], v[200:203], v[20:23]
	v_mfma_f32_16x16x32_bf16 v[56:59], v[240:243], v[208:211], v[56:59]
	v_mfma_f32_16x16x32_bf16 v[24:27], v[248:251], v[208:211], v[24:27]
	v_mfma_f32_16x16x32_bf16 v[60:63], v[240:243], v[230:233], v[60:63]
	v_mfma_f32_16x16x32_bf16 v[28:31], v[248:251], v[230:233], v[28:31]
	s_barrier
	ds_read_b128 v[144:147], v178 offset:49152
	ds_read_b128 v[148:151], v178 offset:50176
	ds_read_b128 v[184:187], v178 offset:51200
	ds_read_b128 v[200:203], v178 offset:52224
	ds_read_b128 v[204:207], v178 offset:53248
	ds_read_b128 v[208:211], v178 offset:54272
	ds_read_b128 v[212:215], v178 offset:55296
	ds_read_b128 v[230:233], v178 offset:56320
	s_add_u32 s48, s80, 0x4000
	s_addc_u32 s49, s81, 0
	s_mov_b32 m0, s24
	s_nop 0
	global_load_lds_dwordx4 v152, s[48:49]
	s_mov_b32 m0, s37
	s_nop 0
	global_load_lds_dwordx4 v188, s[48:49]
	s_waitcnt vmcnt(10)
	s_barrier
	s_waitcnt lgkmcnt(7)
	v_mfma_f32_16x16x32_bf16 v[100:103], v[128:131], v[144:147], v[100:103]
	v_mfma_f32_16x16x32_bf16 v[64:67], v[136:139], v[144:147], v[64:67]
	s_waitcnt lgkmcnt(5)
	v_mfma_f32_16x16x32_bf16 v[104:107], v[128:131], v[184:187], v[104:107]
	v_mfma_f32_16x16x32_bf16 v[68:71], v[136:139], v[184:187], v[68:71]
	s_waitcnt lgkmcnt(3)
	v_mfma_f32_16x16x32_bf16 v[108:111], v[128:131], v[204:207], v[108:111]
	v_mfma_f32_16x16x32_bf16 v[72:75], v[136:139], v[204:207], v[72:75]
	s_waitcnt lgkmcnt(1)
	v_mfma_f32_16x16x32_bf16 v[112:115], v[128:131], v[212:215], v[112:115]
	v_mfma_f32_16x16x32_bf16 v[76:79], v[136:139], v[212:215], v[76:79]
	v_mfma_f32_16x16x32_bf16 v[100:103], v[132:135], v[148:151], v[100:103]
	v_mfma_f32_16x16x32_bf16 v[64:67], v[140:143], v[148:151], v[64:67]
	v_mfma_f32_16x16x32_bf16 v[104:107], v[132:135], v[200:203], v[104:107]
	v_mfma_f32_16x16x32_bf16 v[68:71], v[140:143], v[200:203], v[68:71]
	v_mfma_f32_16x16x32_bf16 v[108:111], v[132:135], v[208:211], v[108:111]
	v_mfma_f32_16x16x32_bf16 v[72:75], v[140:143], v[208:211], v[72:75]
	s_waitcnt lgkmcnt(0)
	v_mfma_f32_16x16x32_bf16 v[112:115], v[132:135], v[230:233], v[112:115]
	v_mfma_f32_16x16x32_bf16 v[76:79], v[140:143], v[230:233], v[76:79]
	s_barrier
	ds_read_b128 v[128:131], v177
	ds_read_b128 v[132:135], v177 offset:1024
	ds_read_b128 v[136:139], v177 offset:2048
	ds_read_b128 v[140:143], v177 offset:3072
	s_add_u32 s48, s76, 0x84000
	s_addc_u32 s49, s77, 0
	s_mov_b32 m0, s97
	s_nop 0
	global_load_lds_dwordx4 v152, s[48:49]
	s_mov_b32 m0, s38
	s_nop 0
	global_load_lds_dwordx4 v188, s[48:49]
	s_add_u32 s48, s80, 0x84000
	s_addc_u32 s49, s81, 0
	s_mov_b32 m0, s34
	s_nop 0
	global_load_lds_dwordx4 v152, s[48:49]
	s_mov_b32 m0, s25
	s_nop 0
	global_load_lds_dwordx4 v188, s[48:49]
	s_waitcnt vmcnt(12)
	s_barrier
	v_mfma_f32_16x16x32_bf16 v[32:35], v[236:239], v[144:147], v[32:35]
	v_mfma_f32_16x16x32_bf16 v[0:3], v[244:247], v[144:147], v[0:3]
	v_mfma_f32_16x16x32_bf16 v[36:39], v[236:239], v[184:187], v[36:39]
	v_mfma_f32_16x16x32_bf16 v[4:7], v[244:247], v[184:187], v[4:7]
	v_mfma_f32_16x16x32_bf16 v[40:43], v[236:239], v[204:207], v[40:43]
	v_mfma_f32_16x16x32_bf16 v[8:11], v[244:247], v[204:207], v[8:11]
	v_mfma_f32_16x16x32_bf16 v[44:47], v[236:239], v[212:215], v[44:47]
	v_mfma_f32_16x16x32_bf16 v[12:15], v[244:247], v[212:215], v[12:15]
	v_mfma_f32_16x16x32_bf16 v[32:35], v[240:243], v[148:151], v[32:35]
	v_mfma_f32_16x16x32_bf16 v[0:3], v[248:251], v[148:151], v[0:3]
	v_mfma_f32_16x16x32_bf16 v[36:39], v[240:243], v[200:203], v[36:39]
	v_mfma_f32_16x16x32_bf16 v[4:7], v[248:251], v[200:203], v[4:7]
	v_mfma_f32_16x16x32_bf16 v[40:43], v[240:243], v[208:211], v[40:43]
	v_mfma_f32_16x16x32_bf16 v[8:11], v[248:251], v[208:211], v[8:11]
	v_mfma_f32_16x16x32_bf16 v[44:47], v[240:243], v[230:233], v[44:47]
	v_mfma_f32_16x16x32_bf16 v[12:15], v[248:251], v[230:233], v[12:15]
	s_add_i32 s71, s71, 2
	s_add_u32 s1, s1, 0x8000
	s_addc_u32 s9, s9, 0
	s_cmp_gt_u32 s71, 29
	s_mov_b64 s[76:77], s[78:79]
	s_barrier
	s_cbranch_scc1 .LBB0_741
